# norm phases second pass: gain/shift/scale pieces for column blocks 1-3 loaded together with block 0
# baseline (speedup 1.0000x reference)
; __device__ __forceinline__ unsigned pk2(float lo, float hi) { return f2bf(lo) | (f2bf(hi) << 16); }
; #define c opq(blockIdx.x)
; __device__ __forceinline__ void phase_norm_mod(const float* srcL, const float* srcC, const float* g, const float* mod_sh, const float* mod_sc, bf16_t* dst, int nrows, const float* part = nullptr, const float* pgate = nullptr, const bf16_t* srcLb = nullptr) {
;     ...
;         const bool isc = row >= NLAT; const float* src = isc ? srcC + (size_t)(row - NLAT) * DM : srcL + (size_t)row * DM; const int ridx = isc ? 4 : (row >> 12);
;         f32x4 v[8]; float s = 0.f;
; #pragma unroll
;         for (int j = 0; j < 8; ++j) {
;             if (srcLb != nullptr && !isc) { const unsigned long long w = *(const unsigned long long*)(srcLb + (size_t)row * DM + j * 256 + lane * 4); const unsigned lo = (unsigned)w, hi = (unsigned)(w >> 32);
;                 v[j] = (f32x4){__uint_as_float(lo << 16), __uint_as_float(lo & 0xffff0000u), __uint_as_float(hi << 16), __uint_as_float(hi & 0xffff0000u)}; }
;             else if (srcLb == nullptr && !isc) v[j] = __builtin_nontemporal_load((const f32x4*)(src + j * 256 + lane * 4));
;             else v[j] = *(const f32x4*)(src + j * 256 + lane * 4);
;             if (part != nullptr && isc) { const size_t po = (size_t)(row - NLAT) * DM + j * 256 + lane * 4; f32x4 ps = *(const f32x4*)(part + po);
; #pragma unroll
;                 for (int p = 1; p < 8; ++p) ps = ps + *(const f32x4*)(part + (size_t)p * (1024 * 2048) + po);
;                 v[j] = v[j] + ps * *(const f32x4*)(pgate + 4 * 12288 + j * 256 + lane * 4); }
;             s += (v[j].x * v[j].x + v[j].y * v[j].y) + (v[j].z * v[j].z + v[j].w * v[j].w); }
;         const float rstd = rsqrtf(wave_sum(s) * (1.f / DM) + 1e-6f);
;         const float* sh = mod_sh + (size_t)ridx * 12288; const float* sc = mod_sc + (size_t)ridx * 12288;
; #pragma unroll
;         for (int j = 0; j < 8; ++j) { const int c = j * 256 + lane * 4; const f32x4 gv = *(const f32x4*)(g + c), shv = *(const f32x4*)(sh + c), scv = *(const f32x4*)(sc + c);
;             const f32x4 y = (v[j] * rstd) * gv; const f32x4 h = y * (scv + 1.f) + shv;
;             u32x2 o; o.x = pk2(h.x, h.y); o.y = pk2(h.z, h.w); *(u32x2*)(dst + (size_t)row * DM + c) = o; }
.LBB0_137:
	s_or_b64 exec, exec, s[8:9]
	v_lshl_add_u64 v[0:1], v[0:1], 0, v[50:51]
	global_load_dwordx4 v[28:31], v[0:1], off
	global_load_dwordx4 v[24:27], v[0:1], off offset:1024
	global_load_dwordx4 v[20:23], v[0:1], off offset:2048
	global_load_dwordx4 v[16:19], v[0:1], off offset:3072
	s_movk_i32 s6, 0x1000
	v_add_co_u32_e32 v0, vcc, s6, v0
	v_lshlrev_b64 v[64:65], 12, v[2:3]
	s_nop 0
	v_addc_co_u32_e32 v1, vcc, 0, v1, vcc
	global_load_dwordx4 v[12:15], v[0:1], off
	s_mov_b32 s6, 0x800000
	v_min_i32_e32 v68, 0x4000, v32
	v_lshl_add_u64 v[32:33], v[32:33], 0, s[78:79]
	v_lshl_add_u64 v[48:49], v[48:49], 0, s[16:17]
	s_waitcnt vmcnt(4)
	v_mov_b32_e32 v4, v29
	s_waitcnt vmcnt(3)
	v_mov_b32_e32 v5, v25
	v_mov_b32_e32 v2, v28
	v_mov_b32_e32 v3, v24
	v_pk_mul_f32 v[4:5], v[4:5], v[4:5]
	v_mov_b32_e32 v6, v31
	v_mov_b32_e32 v7, v27
	v_pk_fma_f32 v[2:3], v[2:3], v[2:3], v[4:5]
	v_mov_b32_e32 v4, v30
	v_mov_b32_e32 v5, v26
	v_pk_mul_f32 v[6:7], v[6:7], v[6:7]
	s_nop 0
	v_pk_fma_f32 v[4:5], v[4:5], v[4:5], v[6:7]
	s_waitcnt vmcnt(2)
	v_pk_mul_f32 v[6:7], v[20:21], v[20:21]
	v_pk_add_f32 v[2:3], v[2:3], v[4:5]
	v_pk_mul_f32 v[4:5], v[22:23], v[22:23]
	v_pk_add_f32 v[2:3], v[2:3], v[2:3] op_sel:[0,1] op_sel_hi:[1,0]
	v_pk_mov_b32 v[8:9], v[6:7], v[4:5] op_sel:[1,0]
	v_mov_b32_e32 v7, v5
	v_pk_add_f32 v[4:5], v[8:9], v[6:7]
	s_waitcnt vmcnt(0)
	v_mul_f32_e32 v6, v12, v12
	v_mul_f32_e32 v7, v13, v13
	v_pk_add_f32 v[4:5], v[4:5], v[4:5] op_sel:[0,1] op_sel_hi:[1,0]
	v_mov_b32_e32 v3, v6
	v_mov_b32_e32 v5, v7
	v_pk_add_f32 v[2:3], v[2:3], v[4:5]
	v_mul_f32_e32 v4, v17, v17
	v_mul_f32_e32 v6, v19, v19
	v_mul_f32_e32 v8, v14, v14
	v_mul_f32_e32 v9, v15, v15
	v_pk_fma_f32 v[4:5], v[16:17], v[16:17], v[4:5] op_sel_hi:[1,1,0]
	v_pk_fma_f32 v[6:7], v[18:19], v[18:19], v[6:7] op_sel_hi:[1,1,0]
	v_mov_b32_e32 v5, v8
	v_mov_b32_e32 v7, v9
	global_load_dwordx4 v[8:11], v[0:1], off offset:1024
	v_pk_add_f32 v[4:5], v[4:5], v[6:7]
	s_nop 0
	v_pk_add_f32 v[60:61], v[2:3], v[4:5]
	s_waitcnt vmcnt(0)
	v_pk_mul_f32 v[2:3], v[10:11], v[10:11]
	v_pk_mul_f32 v[4:5], v[8:9], v[8:9]
	v_pk_add_f32 v[60:61], v[60:61], v[60:61] op_sel:[0,1] op_sel_hi:[1,0]
	v_pk_mov_b32 v[6:7], v[4:5], v[2:3] op_sel:[1,0]
	v_mov_b32_e32 v5, v3
	v_pk_add_f32 v[62:63], v[6:7], v[4:5]
	global_load_dwordx4 v[4:7], v[0:1], off offset:2048
	s_nop 0
	global_load_dwordx4 v[0:3], v[0:1], off offset:3072
	v_pk_add_f32 v[62:63], v[62:63], v[62:63] op_sel:[0,1] op_sel_hi:[1,0]
	global_load_dwordx4 v[78:81], v[36:37], off
	s_waitcnt vmcnt(1)
	v_mul_f32_e32 v34, v0, v0
	v_mul_f32_e32 v66, v1, v1
	v_mov_b32_e32 v61, v34
	v_mov_b32_e32 v63, v66
	v_mul_f32_e32 v34, v5, v5
	v_mul_f32_e32 v67, v2, v2
	v_pk_add_f32 v[60:61], v[60:61], v[62:63]
	v_pk_fma_f32 v[62:63], v[4:5], v[4:5], v[34:35] op_sel_hi:[1,1,0]
	v_mul_f32_e32 v34, v7, v7
	v_mul_f32_e32 v69, v3, v3
	v_mov_b32_e32 v63, v67
	v_pk_fma_f32 v[66:67], v[6:7], v[6:7], v[34:35] op_sel_hi:[1,1,0]
	s_nop 0
	v_mov_b32_e32 v67, v69
	v_pk_add_f32 v[62:63], v[62:63], v[66:67]
	s_nop 0
	v_pk_add_f32 v[60:61], v[60:61], v[62:63]
	s_nop 0
	v_add_f32_e32 v34, v60, v61
	ds_bpermute_b32 v61, v70, v34
	v_ashrrev_i32_e32 v60, 12, v68
	s_waitcnt lgkmcnt(0)
	v_add_f32_e32 v34, v34, v61
	ds_bpermute_b32 v61, v71, v34
	s_waitcnt lgkmcnt(0)
	v_add_f32_e32 v34, v34, v61
	ds_bpermute_b32 v61, v72, v34
	s_waitcnt lgkmcnt(0)
	v_add_f32_e32 v34, v34, v61
	ds_bpermute_b32 v61, v73, v34
	s_waitcnt lgkmcnt(0)
	v_add_f32_e32 v34, v34, v61
	ds_bpermute_b32 v61, v74, v34
	s_waitcnt lgkmcnt(0)
	v_add_f32_e32 v34, v34, v61
	ds_bpermute_b32 v61, v75, v34
	s_waitcnt lgkmcnt(0)
	v_add_f32_e32 v34, v34, v61
	v_fmamk_f32 v34, v34, 0x3a000000, v76
	v_cmp_gt_f32_e32 vcc, s6, v34
	v_mul_f32_e32 v61, 0x4b800000, v34
	s_movk_i32 s6, 0x43ff
	v_cndmask_b32_e32 v34, v34, v61, vcc
	v_rsq_f32_e32 v34, v34
	s_nop 0
	v_mul_f32_e32 v61, 0x45800000, v34
	v_cndmask_b32_e32 v34, v34, v61, vcc
	v_mul_hi_i32_i24_e32 v61, 0x3000, v60
	v_mul_i32_i24_e32 v60, 0x3000, v60
	v_lshlrev_b64 v[60:61], 2, v[60:61]
	v_lshl_add_u64 v[62:63], s[12:13], 0, v[60:61]
	v_lshl_add_u64 v[60:61], s[14:15], 0, v[60:61]
	v_lshl_add_u64 v[68:69], v[60:61], 0, v[50:51]
	v_lshl_add_u64 v[66:67], v[62:63], 0, v[50:51]
	global_load_dwordx4 v[86:89], v[68:69], off
	global_load_dwordx4 v[82:85], v[66:67], off
	global_load_dwordx4 v[120:123], v[36:37], off offset:1024
	global_load_dwordx4 v[124:127], v[66:67], off offset:1024
	global_load_dwordx4 v[128:131], v[68:69], off offset:1024
	global_load_dwordx4 v[132:135], v[36:37], off offset:2048
	global_load_dwordx4 v[136:139], v[66:67], off offset:2048
	global_load_dwordx4 v[140:143], v[68:69], off offset:2048
	global_load_dwordx4 v[144:147], v[36:37], off offset:3072
	global_load_dwordx4 v[148:151], v[66:67], off offset:3072
	global_load_dwordx4 v[152:155], v[68:69], off offset:3072
	v_pk_mul_f32 v[30:31], v[30:31], v[34:35] op_sel_hi:[1,0]
	v_pk_mul_f32 v[28:29], v[28:29], v[34:35] op_sel_hi:[1,0]
	s_waitcnt vmcnt(2)
	v_pk_mul_f32 v[30:31], v[80:81], v[30:31]
	v_pk_mul_f32 v[28:29], v[78:79], v[28:29]
	v_pk_mul_f32 v[24:25], v[24:25], v[34:35] op_sel_hi:[1,0]
	v_pk_mul_f32 v[26:27], v[26:27], v[34:35] op_sel_hi:[1,0]
	v_pk_mul_f32 v[22:23], v[22:23], v[34:35] op_sel_hi:[1,0]
	v_pk_mul_f32 v[20:21], v[20:21], v[34:35] op_sel_hi:[1,0]
	v_pk_mul_f32 v[18:19], v[18:19], v[34:35] op_sel_hi:[1,0]
	v_pk_mul_f32 v[16:17], v[16:17], v[34:35] op_sel_hi:[1,0]
	v_pk_mul_f32 v[14:15], v[14:15], v[34:35] op_sel_hi:[1,0]
	v_pk_mul_f32 v[12:13], v[12:13], v[34:35] op_sel_hi:[1,0]
	v_pk_mul_f32 v[10:11], v[10:11], v[34:35] op_sel_hi:[1,0]
	v_pk_mul_f32 v[8:9], v[8:9], v[34:35] op_sel_hi:[1,0]
	v_pk_mul_f32 v[6:7], v[6:7], v[34:35] op_sel_hi:[1,0]
	v_pk_mul_f32 v[4:5], v[4:5], v[34:35] op_sel_hi:[1,0]
	v_pk_mul_f32 v[2:3], v[2:3], v[34:35] op_sel_hi:[1,0]
	v_pk_mul_f32 v[0:1], v[0:1], v[34:35] op_sel_hi:[1,0]
	v_cmp_lt_i32_e32 vcc, s6, v32
	s_or_b64 s[18:19], vcc, s[18:19]
	s_waitcnt vmcnt(1)
; __device__ __forceinline__ unsigned pk2(float lo, float hi) { return f2bf(lo) | (f2bf(hi) << 16); }
; #define c opq(blockIdx.x)
; __device__ __forceinline__ void phase_norm_mod(const float* srcL, const float* srcC, const float* g, const float* mod_sh, const float* mod_sc, bf16_t* dst, int nrows, const float* part = nullptr, const float* pgate = nullptr, const bf16_t* srcLb = nullptr) {
;     ...
;         for (int j = 0; j < 8; ++j) { const int c = j * 256 + lane * 4; const f32x4 gv = *(const f32x4*)(g + c), shv = *(const f32x4*)(sh + c), scv = *(const f32x4*)(sc + c);
;             const f32x4 y = (v[j] * rstd) * gv; const f32x4 h = y * (scv + 1.f) + shv;
;             u32x2 o; o.x = pk2(h.x, h.y); o.y = pk2(h.z, h.w); *(u32x2*)(dst + (size_t)row * DM + c) = o; }
	v_pk_add_f32 v[80:81], v[86:87], 1.0 op_sel_hi:[1,0]
	v_pk_add_f32 v[78:79], v[88:89], 1.0 op_sel_hi:[1,0]
	s_waitcnt vmcnt(0)
	v_pk_fma_f32 v[28:29], v[80:81], v[28:29], v[82:83]
	v_pk_fma_f32 v[78:79], v[78:79], v[30:31], v[84:85]
	v_bfe_u32 v30, v28, 16, 1
	v_add3_u32 v28, v28, v30, s0
	v_bfe_u32 v30, v29, 16, 1
	v_lshrrev_b32_e32 v28, 16, v28
	v_add3_u32 v29, v29, v30, s0
	v_and_or_b32 v30, v29, s1, v28
	v_bfe_u32 v28, v78, 16, 1
	v_add3_u32 v28, v78, v28, s0
	v_bfe_u32 v29, v79, 16, 1
	v_lshrrev_b32_e32 v28, 16, v28
	v_add3_u32 v29, v79, v29, s0
	v_and_or_b32 v31, v29, s1, v28
	v_lshl_add_u64 v[28:29], v[46:47], 0, v[64:65]
	global_store_dwordx2 v[28:29], v[30:31], off
	v_mov_b32_e32 v78, v120
	v_mov_b32_e32 v79, v121
	v_mov_b32_e32 v80, v122
	v_mov_b32_e32 v81, v123
	v_mov_b32_e32 v82, v124
	v_mov_b32_e32 v83, v125
	v_mov_b32_e32 v84, v126
	v_mov_b32_e32 v85, v127
	v_mov_b32_e32 v86, v128
	v_mov_b32_e32 v87, v129
	v_mov_b32_e32 v88, v130
	v_mov_b32_e32 v89, v131
	v_pk_mul_f32 v[24:25], v[78:79], v[24:25]
	v_pk_mul_f32 v[26:27], v[80:81], v[26:27]
	v_pk_add_f32 v[64:65], v[86:87], 1.0 op_sel_hi:[1,0]
	v_pk_add_f32 v[30:31], v[88:89], 1.0 op_sel_hi:[1,0]
	v_pk_fma_f32 v[24:25], v[64:65], v[24:25], v[82:83]
	v_pk_fma_f32 v[26:27], v[30:31], v[26:27], v[84:85]
	v_bfe_u32 v30, v24, 16, 1
	v_add3_u32 v24, v24, v30, s0
	v_bfe_u32 v30, v25, 16, 1
	v_lshrrev_b32_e32 v24, 16, v24
	v_add3_u32 v25, v25, v30, s0
	v_and_or_b32 v24, v25, s1, v24
	v_bfe_u32 v25, v26, 16, 1
	v_add3_u32 v25, v26, v25, s0
	v_bfe_u32 v26, v27, 16, 1
	v_lshrrev_b32_e32 v25, 16, v25
	v_add3_u32 v26, v27, v26, s0
	v_and_or_b32 v25, v26, s1, v25
	global_store_dwordx2 v[28:29], v[24:25], off offset:512
	v_mov_b32_e32 v24, v132
	v_mov_b32_e32 v25, v133
	v_mov_b32_e32 v26, v134
	v_mov_b32_e32 v27, v135
	s_nop 0
	v_mov_b32_e32 v78, v136
	v_mov_b32_e32 v79, v137
	v_mov_b32_e32 v80, v138
	v_mov_b32_e32 v81, v139
	v_mov_b32_e32 v82, v140
	v_mov_b32_e32 v83, v141
	v_mov_b32_e32 v84, v142
	v_mov_b32_e32 v85, v143
	v_pk_mul_f32 v[20:21], v[24:25], v[20:21]
	v_pk_mul_f32 v[22:23], v[26:27], v[22:23]
	v_pk_add_f32 v[26:27], v[82:83], 1.0 op_sel_hi:[1,0]
	v_pk_add_f32 v[24:25], v[84:85], 1.0 op_sel_hi:[1,0]
	v_pk_fma_f32 v[20:21], v[26:27], v[20:21], v[78:79]
	v_pk_fma_f32 v[22:23], v[24:25], v[22:23], v[80:81]
	v_bfe_u32 v24, v20, 16, 1
	v_add3_u32 v20, v20, v24, s0
	v_bfe_u32 v24, v21, 16, 1
	v_lshrrev_b32_e32 v20, 16, v20
	v_add3_u32 v21, v21, v24, s0
	v_and_or_b32 v20, v21, s1, v20
	v_bfe_u32 v21, v22, 16, 1
	v_add3_u32 v21, v22, v21, s0
	v_bfe_u32 v22, v23, 16, 1
	v_lshrrev_b32_e32 v21, 16, v21
	v_add3_u32 v22, v23, v22, s0
	v_and_or_b32 v21, v22, s1, v21
	global_store_dwordx2 v[28:29], v[20:21], off offset:1024
	v_mov_b32_e32 v20, v144
	v_mov_b32_e32 v21, v145
	v_mov_b32_e32 v22, v146
	v_mov_b32_e32 v23, v147
	s_nop 0
	v_mov_b32_e32 v24, v148
	v_mov_b32_e32 v25, v149
	v_mov_b32_e32 v26, v150
	v_mov_b32_e32 v27, v151
	s_nop 0
	v_mov_b32_e32 v64, v152
	v_mov_b32_e32 v65, v153
	v_mov_b32_e32 v66, v154
	v_mov_b32_e32 v67, v155
	v_pk_mul_f32 v[16:17], v[20:21], v[16:17]
	v_pk_mul_f32 v[18:19], v[22:23], v[18:19]
	v_pk_add_f32 v[22:23], v[64:65], 1.0 op_sel_hi:[1,0]
	v_pk_add_f32 v[20:21], v[66:67], 1.0 op_sel_hi:[1,0]
	v_pk_fma_f32 v[16:17], v[16:17], v[22:23], v[24:25]
	v_pk_fma_f32 v[18:19], v[18:19], v[20:21], v[26:27]
	v_bfe_u32 v20, v16, 16, 1
	v_add3_u32 v16, v16, v20, s0
	v_bfe_u32 v20, v17, 16, 1
	v_lshrrev_b32_e32 v16, 16, v16
	v_add3_u32 v17, v17, v20, s0
	v_and_or_b32 v16, v17, s1, v16
	v_bfe_u32 v17, v18, 16, 1
	v_add3_u32 v17, v18, v17, s0
	v_bfe_u32 v18, v19, 16, 1
	v_lshrrev_b32_e32 v17, 16, v17
	v_add3_u32 v18, v19, v18, s0
	v_and_or_b32 v17, v18, s1, v17
	global_store_dwordx2 v[28:29], v[16:17], off offset:1536
	v_lshl_add_u64 v[24:25], v[60:61], 0, v[52:53]
	global_load_dwordx4 v[16:19], v[38:39], off
	v_lshl_add_u64 v[20:21], v[62:63], 0, v[52:53]
	global_load_dwordx4 v[24:27], v[24:25], off
	s_waitcnt vmcnt(1)
; __device__ __forceinline__ unsigned pk2(float lo, float hi) { return f2bf(lo) | (f2bf(hi) << 16); }
; #define c opq(blockIdx.x)
; __device__ __forceinline__ void phase_norm_mod(const float* srcL, const float* srcC, const float* g, const float* mod_sh, const float* mod_sc, bf16_t* dst, int nrows, const float* part = nullptr, const float* pgate = nullptr, const bf16_t* srcLb = nullptr) {
;     ...
;         for (int j = 0; j < 8; ++j) { const int c = j * 256 + lane * 4; const f32x4 gv = *(const f32x4*)(g + c), shv = *(const f32x4*)(sh + c), scv = *(const f32x4*)(sc + c);
;             const f32x4 y = (v[j] * rstd) * gv; const f32x4 h = y * (scv + 1.f) + shv;
;             u32x2 o; o.x = pk2(h.x, h.y); o.y = pk2(h.z, h.w); *(u32x2*)(dst + (size_t)row * DM + c) = o; }
	v_pk_mul_f32 v[12:13], v[12:13], v[16:17]
	global_load_dwordx4 v[20:23], v[20:21], off
	v_pk_mul_f32 v[14:15], v[14:15], v[18:19]
	s_waitcnt vmcnt(1)
	v_pk_add_f32 v[18:19], v[24:25], 1.0 op_sel_hi:[1,0]
	v_pk_add_f32 v[16:17], v[26:27], 1.0 op_sel_hi:[1,0]
	s_waitcnt vmcnt(0)
	v_pk_fma_f32 v[12:13], v[12:13], v[18:19], v[20:21]
	v_pk_fma_f32 v[14:15], v[14:15], v[16:17], v[22:23]
	v_bfe_u32 v16, v12, 16, 1
	v_add3_u32 v12, v12, v16, s0
	v_bfe_u32 v16, v13, 16, 1
	v_lshrrev_b32_e32 v12, 16, v12
	v_add3_u32 v13, v13, v16, s0
	v_and_or_b32 v12, v13, s1, v12
	v_bfe_u32 v13, v14, 16, 1
	v_add3_u32 v13, v14, v13, s0
	v_bfe_u32 v14, v15, 16, 1
	v_lshrrev_b32_e32 v13, 16, v13
	v_add3_u32 v14, v15, v14, s0
	v_and_or_b32 v13, v14, s1, v13
	global_store_dwordx2 v[28:29], v[12:13], off offset:2048
	v_lshl_add_u64 v[20:21], v[60:61], 0, v[54:55]
	global_load_dwordx4 v[12:15], v[40:41], off
	v_lshl_add_u64 v[16:17], v[62:63], 0, v[54:55]
	global_load_dwordx4 v[20:23], v[20:21], off
	s_waitcnt vmcnt(1)
	v_pk_mul_f32 v[8:9], v[8:9], v[12:13]
	global_load_dwordx4 v[16:19], v[16:17], off
	v_pk_mul_f32 v[10:11], v[10:11], v[14:15]
	s_waitcnt vmcnt(1)
	v_pk_add_f32 v[14:15], v[20:21], 1.0 op_sel_hi:[1,0]
	v_pk_add_f32 v[12:13], v[22:23], 1.0 op_sel_hi:[1,0]
	s_waitcnt vmcnt(0)
	v_pk_fma_f32 v[8:9], v[8:9], v[14:15], v[16:17]
	v_pk_fma_f32 v[10:11], v[10:11], v[12:13], v[18:19]
	v_bfe_u32 v12, v8, 16, 1
	v_add3_u32 v8, v8, v12, s0
	v_bfe_u32 v12, v9, 16, 1
	v_lshrrev_b32_e32 v8, 16, v8
	v_add3_u32 v9, v9, v12, s0
	v_and_or_b32 v8, v9, s1, v8
	v_bfe_u32 v9, v10, 16, 1
	v_add3_u32 v9, v10, v9, s0
	v_bfe_u32 v10, v11, 16, 1
	v_lshrrev_b32_e32 v9, 16, v9
	v_add3_u32 v10, v11, v10, s0
	v_and_or_b32 v9, v10, s1, v9
	global_store_dwordx2 v[28:29], v[8:9], off offset:2560
	v_lshl_add_u64 v[16:17], v[60:61], 0, v[56:57]
	global_load_dwordx4 v[8:11], v[42:43], off
	v_lshl_add_u64 v[12:13], v[62:63], 0, v[56:57]
	global_load_dwordx4 v[16:19], v[16:17], off
	s_waitcnt vmcnt(1)
	v_pk_mul_f32 v[4:5], v[4:5], v[8:9]
	global_load_dwordx4 v[12:15], v[12:13], off
	v_pk_mul_f32 v[6:7], v[6:7], v[10:11]
	s_waitcnt vmcnt(1)
	v_pk_add_f32 v[10:11], v[16:17], 1.0 op_sel_hi:[1,0]
	v_pk_add_f32 v[8:9], v[18:19], 1.0 op_sel_hi:[1,0]
	s_waitcnt vmcnt(0)
	v_pk_fma_f32 v[4:5], v[4:5], v[10:11], v[12:13]
	v_pk_fma_f32 v[6:7], v[6:7], v[8:9], v[14:15]
	v_bfe_u32 v8, v4, 16, 1
	v_add3_u32 v4, v4, v8, s0
	v_bfe_u32 v8, v5, 16, 1
	v_lshrrev_b32_e32 v4, 16, v4
	v_add3_u32 v5, v5, v8, s0
	v_and_or_b32 v4, v5, s1, v4
	v_bfe_u32 v5, v6, 16, 1
	v_add3_u32 v5, v6, v5, s0
	v_bfe_u32 v6, v7, 16, 1
	v_lshrrev_b32_e32 v5, 16, v5
	v_add3_u32 v6, v7, v6, s0
	v_and_or_b32 v5, v6, s1, v5
	global_store_dwordx2 v[28:29], v[4:5], off offset:3072
	v_lshl_add_u64 v[12:13], v[60:61], 0, v[58:59]
	global_load_dwordx4 v[4:7], v[44:45], off
	v_lshl_add_u64 v[8:9], v[62:63], 0, v[58:59]
	global_load_dwordx4 v[12:15], v[12:13], off
	s_waitcnt vmcnt(1)
	v_pk_mul_f32 v[0:1], v[0:1], v[4:5]
	global_load_dwordx4 v[8:11], v[8:9], off
	v_pk_mul_f32 v[2:3], v[2:3], v[6:7]
	s_waitcnt vmcnt(1)
	v_pk_add_f32 v[6:7], v[12:13], 1.0 op_sel_hi:[1,0]
	v_pk_add_f32 v[4:5], v[14:15], 1.0 op_sel_hi:[1,0]
	s_waitcnt vmcnt(0)
	v_pk_fma_f32 v[0:1], v[0:1], v[6:7], v[8:9]
	v_pk_fma_f32 v[2:3], v[2:3], v[4:5], v[10:11]
	v_bfe_u32 v4, v0, 16, 1
	v_add3_u32 v0, v0, v4, s0
	v_bfe_u32 v4, v1, 16, 1
	v_lshrrev_b32_e32 v0, 16, v0
	v_add3_u32 v1, v1, v4, s0
	v_and_or_b32 v0, v1, s1, v0
	v_bfe_u32 v1, v2, 16, 1
	v_add3_u32 v1, v2, v1, s0
	v_bfe_u32 v2, v3, 16, 1
	v_lshrrev_b32_e32 v1, 16, v1
	v_add3_u32 v2, v3, v2, s0
	v_and_or_b32 v1, v2, s1, v1
	global_store_dwordx2 v[28:29], v[0:1], off offset:3584
	s_andn2_b64 exec, exec, s[18:19]
	s_cbranch_execz .LBB0_140

; __device__ __forceinline__ unsigned pk2(float lo, float hi) { return f2bf(lo) | (f2bf(hi) << 16); }
; #define c opq(blockIdx.x)
; __device__ __forceinline__ void phase_norm_mod(const float* srcL, const float* srcC, const float* g, const float* mod_sh, const float* mod_sc, bf16_t* dst, int nrows, const float* part = nullptr, const float* pgate = nullptr, const bf16_t* srcLb = nullptr) {
;     ...
;             s += (v[j].x * v[j].x + v[j].y * v[j].y) + (v[j].z * v[j].z + v[j].w * v[j].w); }
;         const float rstd = rsqrtf(wave_sum(s) * (1.f / DM) + 1e-6f);
;         const float* sh = mod_sh + (size_t)ridx * 12288; const float* sc = mod_sc + (size_t)ridx * 12288;
; #pragma unroll
;         for (int j = 0; j < 8; ++j) { const int c = j * 256 + lane * 4; const f32x4 gv = *(const f32x4*)(g + c), shv = *(const f32x4*)(sh + c), scv = *(const f32x4*)(sc + c);
;             const f32x4 y = (v[j] * rstd) * gv; const f32x4 h = y * (scv + 1.f) + shv;
;             u32x2 o; o.x = pk2(h.x, h.y); o.y = pk2(h.z, h.w); *(u32x2*)(dst + (size_t)row * DM + c) = o; }
.LBB0_1152:
	s_or_b64 exec, exec, s[8:9]
	s_waitcnt vmcnt(0)
	v_mul_f32_e32 v53, v25, v25
	v_mul_f32_e32 v55, v27, v27
	v_fmac_f32_e32 v53, v24, v24
	v_fmac_f32_e32 v55, v26, v26
	v_add_f32_e32 v53, v53, v55
	v_mul_f32_e32 v55, v29, v29
	v_mul_f32_e32 v57, v31, v31
	v_fmac_f32_e32 v55, v28, v28
	v_fmac_f32_e32 v57, v30, v30
	v_add_f32_e32 v55, v55, v57
	v_add_f32_e32 v53, v53, v55
	v_mul_f32_e32 v55, v21, v21
	v_mul_f32_e32 v57, v23, v23
	v_fmac_f32_e32 v55, v20, v20
	v_fmac_f32_e32 v57, v22, v22
	v_add_f32_e32 v55, v55, v57
	v_add_f32_e32 v53, v53, v55
	v_mul_f32_e32 v55, v17, v17
	v_mul_f32_e32 v57, v19, v19
	v_fmac_f32_e32 v55, v16, v16
	v_fmac_f32_e32 v57, v18, v18
	v_add_f32_e32 v55, v55, v57
	v_add_f32_e32 v53, v53, v55
	v_mul_f32_e32 v55, v13, v13
	v_mul_f32_e32 v57, v15, v15
	v_fmac_f32_e32 v55, v12, v12
	v_fmac_f32_e32 v57, v14, v14
	v_add_f32_e32 v55, v55, v57
	v_add_f32_e32 v53, v53, v55
	v_mul_f32_e32 v55, v9, v9
	v_mul_f32_e32 v57, v11, v11
	v_fmac_f32_e32 v55, v8, v8
	v_fmac_f32_e32 v57, v10, v10
	v_add_f32_e32 v55, v55, v57
	v_add_f32_e32 v53, v53, v55
	v_mul_f32_e32 v55, v5, v5
	v_mul_f32_e32 v57, v7, v7
	v_fmac_f32_e32 v55, v4, v4
	v_fmac_f32_e32 v57, v6, v6
	v_add_f32_e32 v55, v55, v57
	v_add_f32_e32 v53, v53, v55
	v_min_i32_e32 v55, 0x4000, v32
	v_pk_mul_f32 v[60:61], v[2:3], v[2:3]
	v_pk_mul_f32 v[62:63], v[0:1], v[0:1]
	v_ashrrev_i32_e32 v55, 12, v55
	v_pk_mov_b32 v[64:65], v[62:63], v[60:61] op_sel:[1,0]
	v_mov_b32_e32 v63, v61
	v_pk_add_f32 v[60:61], v[64:65], v[62:63]
	v_mul_hi_i32_i24_e32 v63, 0x3000, v55
	v_mul_i32_i24_e32 v62, 0x3000, v55
	v_lshlrev_b64 v[62:63], 2, v[62:63]
	v_lshl_add_u64 v[64:65], s[12:13], 0, v[62:63]
	v_lshl_add_u64 v[62:63], s[14:15], 0, v[62:63]
	v_lshl_add_u64 v[70:71], v[62:63], 0, v[34:35]
	global_load_dwordx4 v[80:83], v[38:39], off
	v_lshl_add_u64 v[68:69], v[64:65], 0, v[34:35]
	global_load_dwordx4 v[88:91], v[70:71], off
	global_load_dwordx4 v[84:87], v[68:69], off
	global_load_dwordx4 v[120:123], v[38:39], off offset:1024
	global_load_dwordx4 v[124:127], v[68:69], off offset:1024
	global_load_dwordx4 v[128:131], v[70:71], off offset:1024
	global_load_dwordx4 v[132:135], v[38:39], off offset:2048
	global_load_dwordx4 v[136:139], v[68:69], off offset:2048
	global_load_dwordx4 v[140:143], v[70:71], off offset:2048
	global_load_dwordx4 v[144:147], v[38:39], off offset:3072
	global_load_dwordx4 v[148:151], v[68:69], off offset:3072
	global_load_dwordx4 v[152:155], v[70:71], off offset:3072
	v_add_f32_e32 v57, v60, v61
	v_add_f32_e32 v53, v53, v57
	ds_bpermute_b32 v57, v72, v53
	s_mov_b32 s6, 0x800000
	v_mov_b32_e32 v55, v35
	v_mov_b32_e32 v59, v35
	v_lshl_add_u64 v[32:33], v[32:33], 0, s[78:79]
	s_waitcnt lgkmcnt(0)
	v_add_f32_e32 v53, v53, v57
	ds_bpermute_b32 v57, v73, v53
	v_lshl_add_u64 v[50:51], v[50:51], 0, s[16:17]
	s_waitcnt lgkmcnt(0)
	v_add_f32_e32 v53, v53, v57
	ds_bpermute_b32 v57, v74, v53
	s_waitcnt lgkmcnt(0)
	v_add_f32_e32 v53, v53, v57
	ds_bpermute_b32 v57, v75, v53
	s_waitcnt lgkmcnt(0)
	v_add_f32_e32 v53, v53, v57
	ds_bpermute_b32 v57, v76, v53
	s_waitcnt lgkmcnt(0)
	v_add_f32_e32 v53, v53, v57
	ds_bpermute_b32 v57, v77, v53
	s_waitcnt lgkmcnt(0)
	v_add_f32_e32 v53, v53, v57
	v_fmamk_f32 v53, v53, 0x3a000000, v78
	v_cmp_gt_f32_e32 vcc, s6, v53
	v_mul_f32_e32 v57, 0x4b800000, v53
	s_movk_i32 s6, 0x43ff
	v_cndmask_b32_e32 v53, v53, v57, vcc
	v_rsq_f32_e32 v53, v53
	s_nop 0
	v_mul_f32_e32 v57, 0x45800000, v53
	v_cndmask_b32_e32 v60, v53, v57, vcc
	v_pk_mul_f32 v[26:27], v[26:27], v[60:61] op_sel_hi:[1,0]
	v_pk_mul_f32 v[24:25], v[24:25], v[60:61] op_sel_hi:[1,0]
	v_pk_mul_f32 v[28:29], v[28:29], v[60:61] op_sel_hi:[1,0]
	v_pk_mul_f32 v[22:23], v[22:23], v[60:61] op_sel_hi:[1,0]
	v_pk_mul_f32 v[20:21], v[20:21], v[60:61] op_sel_hi:[1,0]
	v_pk_mul_f32 v[18:19], v[18:19], v[60:61] op_sel_hi:[1,0]
	v_pk_mul_f32 v[16:17], v[16:17], v[60:61] op_sel_hi:[1,0]
	v_pk_mul_f32 v[14:15], v[14:15], v[60:61] op_sel_hi:[1,0]
	v_pk_mul_f32 v[12:13], v[12:13], v[60:61] op_sel_hi:[1,0]
	v_pk_mul_f32 v[10:11], v[10:11], v[60:61] op_sel_hi:[1,0]
	v_pk_mul_f32 v[8:9], v[8:9], v[60:61] op_sel_hi:[1,0]
	v_mov_b32_e32 v57, v35
	v_pk_mul_f32 v[6:7], v[6:7], v[60:61] op_sel_hi:[1,0]
	v_pk_mul_f32 v[4:5], v[4:5], v[60:61] op_sel_hi:[1,0]
	v_pk_mul_f32 v[2:3], v[2:3], v[60:61] op_sel_hi:[1,0]
	v_pk_mul_f32 v[0:1], v[0:1], v[60:61] op_sel_hi:[1,0]
	v_cmp_lt_i32_e32 vcc, s6, v32
	s_or_b64 s[18:19], vcc, s[18:19]
	s_waitcnt vmcnt(2)
	v_pk_mul_f32 v[24:25], v[80:81], v[24:25]
	v_pk_mul_f32 v[26:27], v[82:83], v[26:27]
	s_waitcnt vmcnt(1)
	v_pk_add_f32 v[82:83], v[88:89], 1.0 op_sel_hi:[1,0]
	v_pk_add_f32 v[80:81], v[90:91], 1.0 op_sel_hi:[1,0]
	s_waitcnt vmcnt(0)
; __device__ __forceinline__ unsigned pk2(float lo, float hi) { return f2bf(lo) | (f2bf(hi) << 16); }
; #define c opq(blockIdx.x)
; __device__ __forceinline__ void phase_norm_mod(const float* srcL, const float* srcC, const float* g, const float* mod_sh, const float* mod_sc, bf16_t* dst, int nrows, const float* part = nullptr, const float* pgate = nullptr, const bf16_t* srcLb = nullptr) {
;     ...
;         for (int j = 0; j < 8; ++j) { const int c = j * 256 + lane * 4; const f32x4 gv = *(const f32x4*)(g + c), shv = *(const f32x4*)(sh + c), scv = *(const f32x4*)(sc + c);
;             const f32x4 y = (v[j] * rstd) * gv; const f32x4 h = y * (scv + 1.f) + shv;
;             u32x2 o; o.x = pk2(h.x, h.y); o.y = pk2(h.z, h.w); *(u32x2*)(dst + (size_t)row * DM + c) = o; }
	v_pk_fma_f32 v[24:25], v[82:83], v[24:25], v[84:85]
	v_pk_fma_f32 v[26:27], v[80:81], v[26:27], v[86:87]
	v_bfe_u32 v53, v24, 16, 1
	v_add3_u32 v24, v24, v53, s1
	v_bfe_u32 v53, v25, 16, 1
	v_lshrrev_b32_e32 v24, 16, v24
	v_add3_u32 v25, v25, v53, s1
	v_and_or_b32 v80, v25, s0, v24
	v_bfe_u32 v24, v26, 16, 1
	v_add3_u32 v24, v26, v24, s1
	v_bfe_u32 v25, v27, 16, 1
	v_lshrrev_b32_e32 v24, 16, v24
	v_add3_u32 v25, v27, v25, s1
	v_and_or_b32 v81, v25, s0, v24
	v_lshl_add_u64 v[24:25], v[48:49], 0, v[66:67]
	global_store_dwordx2 v[24:25], v[80:81], off
	v_mov_b32_e32 v80, v120
	v_mov_b32_e32 v81, v121
	v_mov_b32_e32 v82, v122
	v_mov_b32_e32 v83, v123
	s_nop 0
	v_mov_b32_e32 v84, v124
	v_mov_b32_e32 v85, v125
	v_mov_b32_e32 v86, v126
	v_mov_b32_e32 v87, v127
	v_mov_b32_e32 v88, v128
	v_mov_b32_e32 v89, v129
	v_mov_b32_e32 v90, v130
	v_mov_b32_e32 v91, v131
	v_pk_mul_f32 v[26:27], v[30:31], v[60:61] op_sel_hi:[1,0]
	v_mov_b32_e32 v53, v35
	v_pk_mul_f32 v[28:29], v[80:81], v[28:29]
	v_pk_mul_f32 v[26:27], v[82:83], v[26:27]
	v_pk_add_f32 v[66:67], v[88:89], 1.0 op_sel_hi:[1,0]
	v_pk_add_f32 v[30:31], v[90:91], 1.0 op_sel_hi:[1,0]
	v_pk_fma_f32 v[28:29], v[66:67], v[28:29], v[84:85]
	v_pk_fma_f32 v[26:27], v[30:31], v[26:27], v[86:87]
	v_bfe_u32 v30, v28, 16, 1
	v_add3_u32 v28, v28, v30, s1
	v_bfe_u32 v30, v29, 16, 1
	v_lshrrev_b32_e32 v28, 16, v28
	v_add3_u32 v29, v29, v30, s1
	v_and_or_b32 v28, v29, s0, v28
	v_bfe_u32 v29, v26, 16, 1
	v_add3_u32 v26, v26, v29, s1
	v_bfe_u32 v29, v27, 16, 1
	v_lshrrev_b32_e32 v26, 16, v26
	v_add3_u32 v27, v27, v29, s1
	v_and_or_b32 v29, v27, s0, v26
	global_store_dwordx2 v[24:25], v[28:29], off offset:512
	v_mov_b32_e32 v26, v132
	v_mov_b32_e32 v27, v133
	v_mov_b32_e32 v28, v134
	v_mov_b32_e32 v29, v135
	s_nop 0
	v_mov_b32_e32 v80, v136
	v_mov_b32_e32 v81, v137
	v_mov_b32_e32 v82, v138
	v_mov_b32_e32 v83, v139
	v_mov_b32_e32 v84, v140
	v_mov_b32_e32 v85, v141
	v_mov_b32_e32 v86, v142
	v_mov_b32_e32 v87, v143
	v_pk_mul_f32 v[20:21], v[26:27], v[20:21]
	v_pk_mul_f32 v[22:23], v[28:29], v[22:23]
	v_pk_add_f32 v[28:29], v[84:85], 1.0 op_sel_hi:[1,0]
	v_pk_add_f32 v[26:27], v[86:87], 1.0 op_sel_hi:[1,0]
	v_pk_fma_f32 v[20:21], v[28:29], v[20:21], v[80:81]
	v_pk_fma_f32 v[22:23], v[26:27], v[22:23], v[82:83]
	v_bfe_u32 v26, v20, 16, 1
	v_add3_u32 v20, v20, v26, s1
	v_bfe_u32 v26, v21, 16, 1
	v_lshrrev_b32_e32 v20, 16, v20
	v_add3_u32 v21, v21, v26, s1
	v_and_or_b32 v20, v21, s0, v20
	v_bfe_u32 v21, v22, 16, 1
	v_add3_u32 v21, v22, v21, s1
	v_bfe_u32 v22, v23, 16, 1
	v_lshrrev_b32_e32 v21, 16, v21
	v_add3_u32 v22, v23, v22, s1
	v_and_or_b32 v21, v22, s0, v21
	global_store_dwordx2 v[24:25], v[20:21], off offset:1024
	v_mov_b32_e32 v20, v144
	v_mov_b32_e32 v21, v145
	v_mov_b32_e32 v22, v146
	v_mov_b32_e32 v23, v147
	s_nop 0
	v_mov_b32_e32 v26, v148
	v_mov_b32_e32 v27, v149
	v_mov_b32_e32 v28, v150
	v_mov_b32_e32 v29, v151
	s_nop 0
	v_mov_b32_e32 v66, v152
	v_mov_b32_e32 v67, v153
	v_mov_b32_e32 v68, v154
	v_mov_b32_e32 v69, v155
	v_pk_mul_f32 v[16:17], v[20:21], v[16:17]
	v_pk_mul_f32 v[18:19], v[22:23], v[18:19]
	v_pk_add_f32 v[22:23], v[66:67], 1.0 op_sel_hi:[1,0]
	v_pk_add_f32 v[20:21], v[68:69], 1.0 op_sel_hi:[1,0]
	v_pk_fma_f32 v[16:17], v[16:17], v[22:23], v[26:27]
	v_pk_fma_f32 v[18:19], v[18:19], v[20:21], v[28:29]
	v_bfe_u32 v20, v16, 16, 1
	v_add3_u32 v16, v16, v20, s1
	v_bfe_u32 v20, v17, 16, 1
	v_lshrrev_b32_e32 v16, 16, v16
	v_add3_u32 v17, v17, v20, s1
	v_and_or_b32 v16, v17, s0, v16
	v_bfe_u32 v17, v18, 16, 1
	v_add3_u32 v17, v18, v17, s1
	v_bfe_u32 v18, v19, 16, 1
	v_lshrrev_b32_e32 v17, 16, v17
	v_add3_u32 v18, v19, v18, s1
	v_and_or_b32 v17, v18, s0, v17
	global_store_dwordx2 v[24:25], v[16:17], off offset:1536
	v_lshl_add_u64 v[26:27], v[62:63], 0, v[52:53]
	global_load_dwordx4 v[16:19], v[40:41], off
	v_lshl_add_u64 v[20:21], v[64:65], 0, v[52:53]
	global_load_dwordx4 v[26:29], v[26:27], off
	s_waitcnt vmcnt(1)
; __device__ __forceinline__ unsigned pk2(float lo, float hi) { return f2bf(lo) | (f2bf(hi) << 16); }
; #define c opq(blockIdx.x)
; __device__ __forceinline__ void phase_norm_mod(const float* srcL, const float* srcC, const float* g, const float* mod_sh, const float* mod_sc, bf16_t* dst, int nrows, const float* part = nullptr, const float* pgate = nullptr, const bf16_t* srcLb = nullptr) {
;     ...
;         for (int j = 0; j < 8; ++j) { const int c = j * 256 + lane * 4; const f32x4 gv = *(const f32x4*)(g + c), shv = *(const f32x4*)(sh + c), scv = *(const f32x4*)(sc + c);
;             const f32x4 y = (v[j] * rstd) * gv; const f32x4 h = y * (scv + 1.f) + shv;
;             u32x2 o; o.x = pk2(h.x, h.y); o.y = pk2(h.z, h.w); *(u32x2*)(dst + (size_t)row * DM + c) = o; }
	v_pk_mul_f32 v[12:13], v[12:13], v[16:17]
	global_load_dwordx4 v[20:23], v[20:21], off
	v_pk_mul_f32 v[14:15], v[14:15], v[18:19]
	s_waitcnt vmcnt(1)
	v_pk_add_f32 v[18:19], v[26:27], 1.0 op_sel_hi:[1,0]
	v_pk_add_f32 v[16:17], v[28:29], 1.0 op_sel_hi:[1,0]
	s_waitcnt vmcnt(0)
	v_pk_fma_f32 v[12:13], v[12:13], v[18:19], v[20:21]
	v_pk_fma_f32 v[14:15], v[14:15], v[16:17], v[22:23]
	v_bfe_u32 v16, v12, 16, 1
	v_add3_u32 v12, v12, v16, s1
	v_bfe_u32 v16, v13, 16, 1
	v_lshrrev_b32_e32 v12, 16, v12
	v_add3_u32 v13, v13, v16, s1
	v_and_or_b32 v12, v13, s0, v12
	v_bfe_u32 v13, v14, 16, 1
	v_add3_u32 v13, v14, v13, s1
	v_bfe_u32 v14, v15, 16, 1
	v_lshrrev_b32_e32 v13, 16, v13
	v_add3_u32 v14, v15, v14, s1
	v_and_or_b32 v13, v14, s0, v13
	global_store_dwordx2 v[24:25], v[12:13], off offset:2048
	v_lshl_add_u64 v[20:21], v[62:63], 0, v[54:55]
	global_load_dwordx4 v[12:15], v[42:43], off
	v_lshl_add_u64 v[16:17], v[64:65], 0, v[54:55]
	global_load_dwordx4 v[20:23], v[20:21], off
	s_waitcnt vmcnt(1)
	v_pk_mul_f32 v[8:9], v[8:9], v[12:13]
	global_load_dwordx4 v[16:19], v[16:17], off
	v_pk_mul_f32 v[10:11], v[10:11], v[14:15]
	s_waitcnt vmcnt(1)
	v_pk_add_f32 v[14:15], v[20:21], 1.0 op_sel_hi:[1,0]
	v_pk_add_f32 v[12:13], v[22:23], 1.0 op_sel_hi:[1,0]
	s_waitcnt vmcnt(0)
	v_pk_fma_f32 v[8:9], v[8:9], v[14:15], v[16:17]
	v_pk_fma_f32 v[10:11], v[10:11], v[12:13], v[18:19]
	v_bfe_u32 v12, v8, 16, 1
	v_add3_u32 v8, v8, v12, s1
	v_bfe_u32 v12, v9, 16, 1
	v_lshrrev_b32_e32 v8, 16, v8
	v_add3_u32 v9, v9, v12, s1
	v_and_or_b32 v8, v9, s0, v8
	v_bfe_u32 v9, v10, 16, 1
	v_add3_u32 v9, v10, v9, s1
	v_bfe_u32 v10, v11, 16, 1
	v_lshrrev_b32_e32 v9, 16, v9
	v_add3_u32 v10, v11, v10, s1
	v_and_or_b32 v9, v10, s0, v9
	global_store_dwordx2 v[24:25], v[8:9], off offset:2560
	v_lshl_add_u64 v[16:17], v[62:63], 0, v[56:57]
	global_load_dwordx4 v[8:11], v[44:45], off
	v_lshl_add_u64 v[12:13], v[64:65], 0, v[56:57]
	global_load_dwordx4 v[16:19], v[16:17], off
	s_waitcnt vmcnt(1)
	v_pk_mul_f32 v[4:5], v[4:5], v[8:9]
	global_load_dwordx4 v[12:15], v[12:13], off
	v_pk_mul_f32 v[6:7], v[6:7], v[10:11]
	s_waitcnt vmcnt(1)
	v_pk_add_f32 v[10:11], v[16:17], 1.0 op_sel_hi:[1,0]
	v_pk_add_f32 v[8:9], v[18:19], 1.0 op_sel_hi:[1,0]
	s_waitcnt vmcnt(0)
	v_pk_fma_f32 v[4:5], v[4:5], v[10:11], v[12:13]
	v_pk_fma_f32 v[6:7], v[6:7], v[8:9], v[14:15]
	v_bfe_u32 v8, v4, 16, 1
	v_add3_u32 v4, v4, v8, s1
	v_bfe_u32 v8, v5, 16, 1
	v_lshrrev_b32_e32 v4, 16, v4
	v_add3_u32 v5, v5, v8, s1
	v_and_or_b32 v4, v5, s0, v4
	v_bfe_u32 v5, v6, 16, 1
	v_add3_u32 v5, v6, v5, s1
	v_bfe_u32 v6, v7, 16, 1
	v_lshrrev_b32_e32 v5, 16, v5
	v_add3_u32 v6, v7, v6, s1
	v_and_or_b32 v5, v6, s0, v5
	global_store_dwordx2 v[24:25], v[4:5], off offset:3072
	v_lshl_add_u64 v[12:13], v[62:63], 0, v[58:59]
	global_load_dwordx4 v[4:7], v[46:47], off
	v_lshl_add_u64 v[8:9], v[64:65], 0, v[58:59]
	global_load_dwordx4 v[12:15], v[12:13], off
	s_waitcnt vmcnt(1)
	v_pk_mul_f32 v[0:1], v[0:1], v[4:5]
	global_load_dwordx4 v[8:11], v[8:9], off
	v_pk_mul_f32 v[2:3], v[2:3], v[6:7]
	s_waitcnt vmcnt(1)
	v_pk_add_f32 v[6:7], v[12:13], 1.0 op_sel_hi:[1,0]
	v_pk_add_f32 v[4:5], v[14:15], 1.0 op_sel_hi:[1,0]
	s_waitcnt vmcnt(0)
	v_pk_fma_f32 v[0:1], v[0:1], v[6:7], v[8:9]
	v_pk_fma_f32 v[2:3], v[2:3], v[4:5], v[10:11]
	v_bfe_u32 v4, v0, 16, 1
	v_add3_u32 v0, v0, v4, s1
	v_bfe_u32 v4, v1, 16, 1
	v_lshrrev_b32_e32 v0, 16, v0
	v_add3_u32 v1, v1, v4, s1
	v_and_or_b32 v0, v1, s0, v0
	v_bfe_u32 v1, v2, 16, 1
	v_add3_u32 v1, v2, v1, s1
	v_bfe_u32 v2, v3, 16, 1
	v_lshrrev_b32_e32 v1, 16, v1
	v_add3_u32 v2, v3, v2, s1
	v_and_or_b32 v1, v2, s0, v1
	global_store_dwordx2 v[24:25], v[0:1], off offset:3584
	s_andn2_b64 exec, exec, s[18:19]
	s_cbranch_execz .LBB0_1187

; __device__ __forceinline__ unsigned pk2(float lo, float hi) { return f2bf(lo) | (f2bf(hi) << 16); }
; #define c opq(blockIdx.x)
; __device__ __forceinline__ void phase_norm_mod(const float* srcL, const float* srcC, const float* g, const float* mod_sh, const float* mod_sc, bf16_t* dst, int nrows, const float* part = nullptr, const float* pgate = nullptr, const bf16_t* srcLb = nullptr) {
;     ...
;             s += (v[j].x * v[j].x + v[j].y * v[j].y) + (v[j].z * v[j].z + v[j].w * v[j].w); }
;         const float rstd = rsqrtf(wave_sum(s) * (1.f / DM) + 1e-6f);
;         const float* sh = mod_sh + (size_t)ridx * 12288; const float* sc = mod_sc + (size_t)ridx * 12288;
; #pragma unroll
;         for (int j = 0; j < 8; ++j) { const int c = j * 256 + lane * 4; const f32x4 gv = *(const f32x4*)(g + c), shv = *(const f32x4*)(sh + c), scv = *(const f32x4*)(sc + c);
;             const f32x4 y = (v[j] * rstd) * gv; const f32x4 h = y * (scv + 1.f) + shv;
;             u32x2 o; o.x = pk2(h.x, h.y); o.y = pk2(h.z, h.w); *(u32x2*)(dst + (size_t)row * DM + c) = o; }
.LBB0_1468:
	s_or_b64 exec, exec, s[8:9]
	s_waitcnt vmcnt(0)
	v_mul_f32_e32 v36, v1, v1
	v_mul_f32_e32 v65, v3, v3
	v_fmac_f32_e32 v36, v0, v0
	v_fmac_f32_e32 v65, v2, v2
	v_add_f32_e32 v36, v36, v65
	v_mul_f32_e32 v65, v5, v5
	v_mul_f32_e32 v67, v7, v7
	v_fmac_f32_e32 v65, v4, v4
	v_fmac_f32_e32 v67, v6, v6
	v_add_f32_e32 v65, v65, v67
	v_add_f32_e32 v36, v36, v65
	v_mul_f32_e32 v65, v9, v9
	v_mul_f32_e32 v67, v11, v11
	v_fmac_f32_e32 v65, v8, v8
	v_fmac_f32_e32 v67, v10, v10
	v_add_f32_e32 v65, v65, v67
	v_add_f32_e32 v36, v36, v65
	v_mul_f32_e32 v65, v13, v13
	v_mul_f32_e32 v67, v15, v15
	v_fmac_f32_e32 v65, v12, v12
	v_fmac_f32_e32 v67, v14, v14
	v_add_f32_e32 v65, v65, v67
	v_add_f32_e32 v36, v36, v65
	v_mul_f32_e32 v65, v17, v17
	v_mul_f32_e32 v67, v19, v19
	v_fmac_f32_e32 v65, v16, v16
	v_fmac_f32_e32 v67, v18, v18
	v_add_f32_e32 v65, v65, v67
	v_add_f32_e32 v36, v36, v65
	v_mul_f32_e32 v65, v21, v21
	v_mul_f32_e32 v67, v23, v23
	v_fmac_f32_e32 v65, v20, v20
	v_fmac_f32_e32 v67, v22, v22
	v_add_f32_e32 v65, v65, v67
	v_add_f32_e32 v36, v36, v65
	v_mul_f32_e32 v65, v25, v25
	v_mul_f32_e32 v67, v27, v27
	v_fmac_f32_e32 v65, v24, v24
	v_fmac_f32_e32 v67, v26, v26
	v_add_f32_e32 v65, v65, v67
	v_pk_mul_f32 v[76:77], v[30:31], v[30:31]
	v_pk_mul_f32 v[78:79], v[28:29], v[28:29]
	v_add_f32_e32 v36, v36, v65
	v_min_i32_e32 v65, 0x4000, v32
	v_pk_mov_b32 v[80:81], v[78:79], v[76:77] op_sel:[1,0]
	v_mov_b32_e32 v79, v77
	v_pk_add_f32 v[76:77], v[80:81], v[78:79]
	v_ashrrev_i32_e32 v65, 12, v65
	v_add_f32_e32 v67, v76, v77
	v_mul_hi_i32_i24_e32 v77, 0x3000, v65
	v_mul_i32_i24_e32 v76, 0x3000, v65
	v_lshlrev_b64 v[76:77], 2, v[76:77]
	v_lshl_add_u64 v[78:79], s[12:13], 0, v[76:77]
	v_lshl_add_u64 v[76:77], s[42:43], 0, v[76:77]
	v_mov_b32_e32 v65, v37
	v_lshl_add_u64 v[82:83], v[76:77], 0, v[64:65]
	global_load_dwordx4 v[90:93], v[42:43], off
	v_lshl_add_u64 v[80:81], v[78:79], 0, v[64:65]
	global_load_dwordx4 v[98:101], v[82:83], off
	global_load_dwordx4 v[94:97], v[80:81], off
	global_load_dwordx4 v[120:123], v[42:43], off offset:1024
	global_load_dwordx4 v[124:127], v[80:81], off offset:1024
	global_load_dwordx4 v[128:131], v[82:83], off offset:1024
	global_load_dwordx4 v[132:135], v[42:43], off offset:2048
	global_load_dwordx4 v[136:139], v[80:81], off offset:2048
	global_load_dwordx4 v[140:143], v[82:83], off offset:2048
	global_load_dwordx4 v[144:147], v[42:43], off offset:3072
	global_load_dwordx4 v[148:151], v[80:81], off offset:3072
	global_load_dwordx4 v[152:155], v[82:83], off offset:3072
	v_add_f32_e32 v36, v36, v67
	ds_bpermute_b32 v67, v35, v36
	v_mov_b32_e32 v69, v37
	v_mov_b32_e32 v71, v37
	v_mov_b32_e32 v73, v37
	v_lshl_add_u64 v[32:33], v[32:33], 0, s[78:79]
	s_waitcnt lgkmcnt(0)
	v_add_f32_e32 v36, v36, v67
	ds_bpermute_b32 v67, v84, v36
	s_movk_i32 s8, 0x43ff
	v_lshl_add_u64 v[62:63], v[62:63], 0, s[46:47]
	s_waitcnt lgkmcnt(0)
	v_add_f32_e32 v36, v36, v67
	ds_bpermute_b32 v67, v85, v36
	s_waitcnt lgkmcnt(0)
	v_add_f32_e32 v36, v36, v67
	ds_bpermute_b32 v67, v86, v36
	s_waitcnt lgkmcnt(0)
	v_add_f32_e32 v36, v36, v67
	ds_bpermute_b32 v67, v87, v36
	s_waitcnt lgkmcnt(0)
	v_add_f32_e32 v36, v36, v67
	ds_bpermute_b32 v67, v88, v36
	s_waitcnt lgkmcnt(0)
	v_add_f32_e32 v36, v36, v67
	v_fmamk_f32 v36, v36, 0x3a000000, v89
	v_cmp_gt_f32_e32 vcc, s1, v36
	v_mul_f32_e32 v67, 0x4b800000, v36
	s_nop 0
	v_cndmask_b32_e32 v36, v36, v67, vcc
	v_rsq_f32_e32 v36, v36
	s_nop 0
	v_mul_f32_e32 v67, 0x45800000, v36
	v_cndmask_b32_e32 v36, v36, v67, vcc
	v_pk_mul_f32 v[2:3], v[2:3], v[36:37] op_sel_hi:[1,0]
	v_pk_mul_f32 v[0:1], v[0:1], v[36:37] op_sel_hi:[1,0]
	v_pk_mul_f32 v[4:5], v[4:5], v[36:37] op_sel_hi:[1,0]
	v_pk_mul_f32 v[8:9], v[8:9], v[36:37] op_sel_hi:[1,0]
	v_pk_mul_f32 v[12:13], v[12:13], v[36:37] op_sel_hi:[1,0]
	v_mov_b32_e32 v67, v37
	v_pk_mul_f32 v[16:17], v[16:17], v[36:37] op_sel_hi:[1,0]
	v_cmp_lt_i32_e32 vcc, s8, v32
	s_or_b64 s[48:49], vcc, s[48:49]
	s_waitcnt vmcnt(2)
	v_pk_mul_f32 v[0:1], v[90:91], v[0:1]
	v_pk_mul_f32 v[2:3], v[92:93], v[2:3]
	s_waitcnt vmcnt(1)
	v_pk_add_f32 v[92:93], v[98:99], 1.0 op_sel_hi:[1,0]
	v_pk_add_f32 v[90:91], v[100:101], 1.0 op_sel_hi:[1,0]
	s_waitcnt vmcnt(0)
	v_pk_fma_f32 v[0:1], v[92:93], v[0:1], v[94:95]
	v_pk_fma_f32 v[2:3], v[90:91], v[2:3], v[96:97]
	v_bfe_u32 v65, v0, 16, 1
	v_add3_u32 v0, v0, v65, s16
	v_bfe_u32 v65, v1, 16, 1
	v_lshrrev_b32_e32 v0, 16, v0
	v_add3_u32 v1, v1, v65, s16
	v_and_or_b32 v90, v1, s0, v0
	v_bfe_u32 v0, v2, 16, 1
	v_add3_u32 v0, v2, v0, s16
	v_bfe_u32 v1, v3, 16, 1
	v_lshrrev_b32_e32 v0, 16, v0
	v_add3_u32 v1, v3, v1, s16
	v_and_or_b32 v91, v1, s0, v0
	v_lshl_add_u64 v[0:1], v[60:61], 0, v[74:75]
	global_store_dwordx2 v[0:1], v[90:91], off
	v_mov_b32_e32 v90, v120
	v_mov_b32_e32 v91, v121
	v_mov_b32_e32 v92, v122
	v_mov_b32_e32 v93, v123
	s_nop 0
	v_mov_b32_e32 v94, v124
	v_mov_b32_e32 v95, v125
	v_mov_b32_e32 v96, v126
	v_mov_b32_e32 v97, v127
	v_mov_b32_e32 v98, v128
	v_mov_b32_e32 v99, v129
	v_mov_b32_e32 v100, v130
	v_mov_b32_e32 v101, v131
	v_pk_mul_f32 v[2:3], v[6:7], v[36:37] op_sel_hi:[1,0]
	v_pk_mul_f32 v[4:5], v[90:91], v[4:5]
	v_pk_mul_f32 v[2:3], v[92:93], v[2:3]
	v_pk_add_f32 v[74:75], v[98:99], 1.0 op_sel_hi:[1,0]
	v_pk_add_f32 v[6:7], v[100:101], 1.0 op_sel_hi:[1,0]
	v_pk_fma_f32 v[4:5], v[74:75], v[4:5], v[94:95]
	v_pk_fma_f32 v[2:3], v[6:7], v[2:3], v[96:97]
	v_bfe_u32 v6, v4, 16, 1
	v_add3_u32 v4, v4, v6, s16
	v_bfe_u32 v6, v5, 16, 1
	v_lshrrev_b32_e32 v4, 16, v4
	v_add3_u32 v5, v5, v6, s16
	v_and_or_b32 v4, v5, s0, v4
	v_bfe_u32 v5, v2, 16, 1
	v_add3_u32 v2, v2, v5, s16
	v_bfe_u32 v5, v3, 16, 1
	v_lshrrev_b32_e32 v2, 16, v2
; __device__ __forceinline__ unsigned pk2(float lo, float hi) { return f2bf(lo) | (f2bf(hi) << 16); }
; #define c opq(blockIdx.x)
; __device__ __forceinline__ void phase_norm_mod(const float* srcL, const float* srcC, const float* g, const float* mod_sh, const float* mod_sc, bf16_t* dst, int nrows, const float* part = nullptr, const float* pgate = nullptr, const bf16_t* srcLb = nullptr) {
;     ...
;         for (int j = 0; j < 8; ++j) { const int c = j * 256 + lane * 4; const f32x4 gv = *(const f32x4*)(g + c), shv = *(const f32x4*)(sh + c), scv = *(const f32x4*)(sc + c);
;             const f32x4 y = (v[j] * rstd) * gv; const f32x4 h = y * (scv + 1.f) + shv;
;             u32x2 o; o.x = pk2(h.x, h.y); o.y = pk2(h.z, h.w); *(u32x2*)(dst + (size_t)row * DM + c) = o; }
	v_add3_u32 v3, v3, v5, s16
	v_and_or_b32 v5, v3, s0, v2
	global_store_dwordx2 v[0:1], v[4:5], off offset:512
	v_mov_b32_e32 v2, v132
	v_mov_b32_e32 v3, v133
	v_mov_b32_e32 v4, v134
	v_mov_b32_e32 v5, v135
	s_nop 0
	v_mov_b32_e32 v90, v136
	v_mov_b32_e32 v91, v137
	v_mov_b32_e32 v92, v138
	v_mov_b32_e32 v93, v139
	v_mov_b32_e32 v94, v140
	v_mov_b32_e32 v95, v141
	v_mov_b32_e32 v96, v142
	v_mov_b32_e32 v97, v143
	v_pk_mul_f32 v[6:7], v[10:11], v[36:37] op_sel_hi:[1,0]
	v_pk_mul_f32 v[10:11], v[14:15], v[36:37] op_sel_hi:[1,0]
	v_pk_mul_f32 v[14:15], v[18:19], v[36:37] op_sel_hi:[1,0]
	v_pk_mul_f32 v[2:3], v[2:3], v[8:9]
	v_pk_mul_f32 v[4:5], v[4:5], v[6:7]
	v_pk_add_f32 v[8:9], v[94:95], 1.0 op_sel_hi:[1,0]
	v_pk_add_f32 v[6:7], v[96:97], 1.0 op_sel_hi:[1,0]
	v_pk_fma_f32 v[2:3], v[8:9], v[2:3], v[90:91]
	v_pk_fma_f32 v[4:5], v[6:7], v[4:5], v[92:93]
	v_bfe_u32 v6, v2, 16, 1
	v_add3_u32 v2, v2, v6, s16
	v_bfe_u32 v6, v3, 16, 1
	v_lshrrev_b32_e32 v2, 16, v2
	v_add3_u32 v3, v3, v6, s16
	v_and_or_b32 v2, v3, s0, v2
	v_bfe_u32 v3, v4, 16, 1
	v_add3_u32 v3, v4, v3, s16
	v_bfe_u32 v4, v5, 16, 1
	v_lshrrev_b32_e32 v3, 16, v3
	v_add3_u32 v4, v5, v4, s16
	v_and_or_b32 v3, v4, s0, v3
	global_store_dwordx2 v[0:1], v[2:3], off offset:1024
	v_mov_b32_e32 v2, v144
	v_mov_b32_e32 v3, v145
	v_mov_b32_e32 v4, v146
	v_mov_b32_e32 v5, v147
	s_nop 0
	v_mov_b32_e32 v6, v148
	v_mov_b32_e32 v7, v149
	v_mov_b32_e32 v8, v150
	v_mov_b32_e32 v9, v151
	s_nop 0
	v_mov_b32_e32 v80, v152
	v_mov_b32_e32 v81, v153
	v_mov_b32_e32 v82, v154
	v_mov_b32_e32 v83, v155
	v_pk_mul_f32 v[2:3], v[2:3], v[12:13]
	v_pk_mul_f32 v[4:5], v[4:5], v[10:11]
	v_pk_add_f32 v[12:13], v[80:81], 1.0 op_sel_hi:[1,0]
	v_pk_add_f32 v[10:11], v[82:83], 1.0 op_sel_hi:[1,0]
	v_pk_fma_f32 v[2:3], v[2:3], v[12:13], v[6:7]
	v_pk_fma_f32 v[4:5], v[4:5], v[10:11], v[8:9]
	v_bfe_u32 v6, v2, 16, 1
	v_add3_u32 v2, v2, v6, s16
	v_bfe_u32 v6, v3, 16, 1
	v_lshrrev_b32_e32 v2, 16, v2
	v_add3_u32 v3, v3, v6, s16
	v_and_or_b32 v2, v3, s0, v2
	v_bfe_u32 v3, v4, 16, 1
	v_add3_u32 v3, v4, v3, s16
	v_bfe_u32 v4, v5, 16, 1
	v_lshrrev_b32_e32 v3, 16, v3
	v_add3_u32 v4, v5, v4, s16
	v_and_or_b32 v3, v4, s0, v3
	global_store_dwordx2 v[0:1], v[2:3], off offset:1536
	v_lshl_add_u64 v[10:11], v[76:77], 0, v[66:67]
	global_load_dwordx4 v[2:5], v[52:53], off
	v_lshl_add_u64 v[6:7], v[78:79], 0, v[66:67]
	global_load_dwordx4 v[10:13], v[10:11], off
	s_waitcnt vmcnt(1)
	v_pk_mul_f32 v[2:3], v[16:17], v[2:3]
	global_load_dwordx4 v[6:9], v[6:7], off
	s_waitcnt vmcnt(1)
	v_pk_add_f32 v[10:11], v[10:11], 1.0 op_sel_hi:[1,0]
	v_pk_mul_f32 v[4:5], v[14:15], v[4:5]
	v_pk_add_f32 v[12:13], v[12:13], 1.0 op_sel_hi:[1,0]
	v_pk_mul_f32 v[16:17], v[20:21], v[36:37] op_sel_hi:[1,0]
	v_pk_mul_f32 v[14:15], v[22:23], v[36:37] op_sel_hi:[1,0]
	s_waitcnt vmcnt(0)
	v_pk_fma_f32 v[2:3], v[2:3], v[10:11], v[6:7]
	s_nop 0
	v_bfe_u32 v6, v2, 16, 1
	v_add3_u32 v2, v2, v6, s16
	v_bfe_u32 v6, v3, 16, 1
	v_pk_fma_f32 v[4:5], v[4:5], v[12:13], v[8:9]
	v_lshrrev_b32_e32 v2, 16, v2
	v_add3_u32 v3, v3, v6, s16
	v_and_or_b32 v2, v3, s0, v2
	v_bfe_u32 v3, v4, 16, 1
	v_add3_u32 v3, v4, v3, s16
	v_bfe_u32 v4, v5, 16, 1
	v_lshrrev_b32_e32 v3, 16, v3
	v_add3_u32 v4, v5, v4, s16
	v_and_or_b32 v3, v4, s0, v3
	global_store_dwordx2 v[0:1], v[2:3], off offset:2048
	v_lshl_add_u64 v[10:11], v[76:77], 0, v[68:69]
	global_load_dwordx4 v[2:5], v[54:55], off
	v_lshl_add_u64 v[6:7], v[78:79], 0, v[68:69]
	global_load_dwordx4 v[10:13], v[10:11], off
	s_waitcnt vmcnt(1)
	v_pk_mul_f32 v[2:3], v[16:17], v[2:3]
	global_load_dwordx4 v[6:9], v[6:7], off
	s_waitcnt vmcnt(1)
	v_pk_add_f32 v[10:11], v[10:11], 1.0 op_sel_hi:[1,0]
	v_pk_mul_f32 v[4:5], v[14:15], v[4:5]
	v_pk_add_f32 v[12:13], v[12:13], 1.0 op_sel_hi:[1,0]
	v_pk_mul_f32 v[16:17], v[24:25], v[36:37] op_sel_hi:[1,0]
	v_pk_mul_f32 v[14:15], v[26:27], v[36:37] op_sel_hi:[1,0]
	s_waitcnt vmcnt(0)
	v_pk_fma_f32 v[2:3], v[2:3], v[10:11], v[6:7]
	s_nop 0
	v_bfe_u32 v6, v2, 16, 1
	v_add3_u32 v2, v2, v6, s16
	v_bfe_u32 v6, v3, 16, 1
	v_pk_fma_f32 v[4:5], v[4:5], v[12:13], v[8:9]
	v_lshrrev_b32_e32 v2, 16, v2
	v_add3_u32 v3, v3, v6, s16
	v_and_or_b32 v2, v3, s0, v2
	v_bfe_u32 v3, v4, 16, 1
	v_add3_u32 v3, v4, v3, s16
	v_bfe_u32 v4, v5, 16, 1
	v_lshrrev_b32_e32 v3, 16, v3
	v_add3_u32 v4, v5, v4, s16
	v_and_or_b32 v3, v4, s0, v3
	global_store_dwordx2 v[0:1], v[2:3], off offset:2560
	v_lshl_add_u64 v[10:11], v[76:77], 0, v[70:71]
	global_load_dwordx4 v[2:5], v[56:57], off
	v_lshl_add_u64 v[6:7], v[78:79], 0, v[70:71]
	global_load_dwordx4 v[10:13], v[10:11], off
	s_waitcnt vmcnt(1)
	v_pk_mul_f32 v[2:3], v[16:17], v[2:3]
	global_load_dwordx4 v[6:9], v[6:7], off
	s_waitcnt vmcnt(1)
	v_pk_add_f32 v[10:11], v[10:11], 1.0 op_sel_hi:[1,0]
	v_pk_mul_f32 v[4:5], v[14:15], v[4:5]
	v_pk_add_f32 v[12:13], v[12:13], 1.0 op_sel_hi:[1,0]
	v_pk_mul_f32 v[16:17], v[28:29], v[36:37] op_sel_hi:[1,0]
	v_pk_mul_f32 v[14:15], v[30:31], v[36:37] op_sel_hi:[1,0]
	s_waitcnt vmcnt(0)
	v_pk_fma_f32 v[2:3], v[2:3], v[10:11], v[6:7]
	s_nop 0
	v_bfe_u32 v6, v2, 16, 1
	v_add3_u32 v2, v2, v6, s16
	v_bfe_u32 v6, v3, 16, 1
	v_pk_fma_f32 v[4:5], v[4:5], v[12:13], v[8:9]
	v_lshrrev_b32_e32 v2, 16, v2
	v_add3_u32 v3, v3, v6, s16
	v_and_or_b32 v2, v3, s0, v2
	v_bfe_u32 v3, v4, 16, 1
	v_add3_u32 v3, v4, v3, s16
	v_bfe_u32 v4, v5, 16, 1
	v_lshrrev_b32_e32 v3, 16, v3
	v_add3_u32 v4, v5, v4, s16
	v_and_or_b32 v3, v4, s0, v3
	global_store_dwordx2 v[0:1], v[2:3], off offset:3072
	v_lshl_add_u64 v[10:11], v[76:77], 0, v[72:73]
	global_load_dwordx4 v[2:5], v[58:59], off
	v_lshl_add_u64 v[6:7], v[78:79], 0, v[72:73]
	global_load_dwordx4 v[10:13], v[10:11], off
	s_waitcnt vmcnt(1)
	v_pk_mul_f32 v[2:3], v[16:17], v[2:3]
	global_load_dwordx4 v[6:9], v[6:7], off
	s_waitcnt vmcnt(1)
	v_pk_add_f32 v[10:11], v[10:11], 1.0 op_sel_hi:[1,0]
	v_pk_mul_f32 v[4:5], v[14:15], v[4:5]
	v_pk_add_f32 v[12:13], v[12:13], 1.0 op_sel_hi:[1,0]
	s_waitcnt vmcnt(0)
	v_pk_fma_f32 v[2:3], v[2:3], v[10:11], v[6:7]
	s_nop 0
	v_bfe_u32 v6, v2, 16, 1
	v_add3_u32 v2, v2, v6, s16
	v_bfe_u32 v6, v3, 16, 1
	v_pk_fma_f32 v[4:5], v[4:5], v[12:13], v[8:9]
	v_lshrrev_b32_e32 v2, 16, v2
	v_add3_u32 v3, v3, v6, s16
	v_and_or_b32 v2, v3, s0, v2
	v_bfe_u32 v3, v4, 16, 1
	v_add3_u32 v3, v4, v3, s16
	v_bfe_u32 v4, v5, 16, 1
	v_lshrrev_b32_e32 v3, 16, v3
	v_add3_u32 v4, v5, v4, s16
	v_and_or_b32 v3, v4, s0, v3
	global_store_dwordx2 v[0:1], v[2:3], off offset:3584
	s_andn2_b64 exec, exec, s[48:49]
	s_cbranch_execz .LBB0_1521

; __device__ __forceinline__ unsigned pk2(float lo, float hi) { return f2bf(lo) | (f2bf(hi) << 16); }
; #define c opq(blockIdx.x)
; __device__ __forceinline__ void phase_norm_mod(const float* srcL, const float* srcC, const float* g, const float* mod_sh, const float* mod_sc, bf16_t* dst, int nrows, const float* part = nullptr, const float* pgate = nullptr, const bf16_t* srcLb = nullptr) {
;     ...
;         const bool isc = row >= NLAT; const float* src = isc ? srcC + (size_t)(row - NLAT) * DM : srcL + (size_t)row * DM; const int ridx = isc ? 4 : (row >> 12);
;         f32x4 v[8]; float s = 0.f;
; #pragma unroll
;         for (int j = 0; j < 8; ++j) {
;             if (srcLb != nullptr && !isc) { const unsigned long long w = *(const unsigned long long*)(srcLb + (size_t)row * DM + j * 256 + lane * 4); const unsigned lo = (unsigned)w, hi = (unsigned)(w >> 32);
;                 v[j] = (f32x4){__uint_as_float(lo << 16), __uint_as_float(lo & 0xffff0000u), __uint_as_float(hi << 16), __uint_as_float(hi & 0xffff0000u)}; }
;             else if (srcLb == nullptr && !isc) v[j] = __builtin_nontemporal_load((const f32x4*)(src + j * 256 + lane * 4));
;             else v[j] = *(const f32x4*)(src + j * 256 + lane * 4);
;             if (part != nullptr && isc) { const size_t po = (size_t)(row - NLAT) * DM + j * 256 + lane * 4; f32x4 ps = *(const f32x4*)(part + po);
; #pragma unroll
;                 for (int p = 1; p < 8; ++p) ps = ps + *(const f32x4*)(part + (size_t)p * (1024 * 2048) + po);
;                 v[j] = v[j] + ps * *(const f32x4*)(pgate + 4 * 12288 + j * 256 + lane * 4); }
;             s += (v[j].x * v[j].x + v[j].y * v[j].y) + (v[j].z * v[j].z + v[j].w * v[j].w); }
;         const float rstd = rsqrtf(wave_sum(s) * (1.f / DM) + 1e-6f);
;         const float* sh = mod_sh + (size_t)ridx * 12288; const float* sc = mod_sc + (size_t)ridx * 12288;
; #pragma unroll
;         for (int j = 0; j < 8; ++j) { const int c = j * 256 + lane * 4; const f32x4 gv = *(const f32x4*)(g + c), shv = *(const f32x4*)(sh + c), scv = *(const f32x4*)(sc + c);
;             const f32x4 y = (v[j] * rstd) * gv; const f32x4 h = y * (scv + 1.f) + shv;
;             u32x2 o; o.x = pk2(h.x, h.y); o.y = pk2(h.z, h.w); *(u32x2*)(dst + (size_t)row * DM + c) = o; }
.LBB0_2178:
	v_lshl_add_u64 v[30:31], v[16:17], 0, v[2:3]
	v_add_co_u32_e32 v30, vcc, 0x26500000, v30
	global_load_dwordx4 v[58:61], v[4:5], off
	s_nop 0
	v_addc_co_u32_e32 v31, vcc, 0, v31, vcc
	global_load_dwordx2 v[38:39], v[30:31], off
	global_load_dwordx2 v[40:41], v[30:31], off offset:512
	global_load_dwordx2 v[44:45], v[30:31], off offset:1024
	global_load_dwordx2 v[46:47], v[30:31], off offset:1536
	global_load_dwordx2 v[50:51], v[30:31], off offset:2048
	global_load_dwordx2 v[70:71], v[30:31], off offset:2560
	global_load_dwordx2 v[72:73], v[30:31], off offset:3072
	global_load_dwordx2 v[74:75], v[30:31], off offset:3584
	v_ashrrev_i32_e32 v32, 12, v0
	v_mul_hi_i32_i24_e32 v33, 0x3000, v32
	v_mul_i32_i24_e32 v32, 0x3000, v32
	v_lshlrev_b64 v[32:33], 2, v[32:33]
	v_lshl_add_u64 v[34:35], s[8:9], 0, v[32:33]
	v_lshl_add_u64 v[36:37], s[4:5], 0, v[32:33]
	v_lshl_add_u64 v[78:79], v[34:35], 0, v[18:19]
	v_lshl_add_u64 v[76:77], v[36:37], 0, v[18:19]
	global_load_dwordx4 v[62:65], v[78:79], off
	global_load_dwordx4 v[66:69], v[76:77], off
	global_load_dwordx4 v[120:123], v[4:5], off offset:1024
	global_load_dwordx4 v[124:127], v[78:79], off offset:1024
	global_load_dwordx4 v[128:131], v[76:77], off offset:1024
	global_load_dwordx4 v[132:135], v[4:5], off offset:2048
	global_load_dwordx4 v[136:139], v[78:79], off offset:2048
	global_load_dwordx4 v[140:143], v[76:77], off offset:2048
	global_load_dwordx4 v[144:147], v[4:5], off offset:3072
	global_load_dwordx4 v[148:151], v[78:79], off offset:3072
	global_load_dwordx4 v[152:155], v[76:77], off offset:3072
	v_lshl_add_u64 v[28:29], v[14:15], 0, v[2:3]
	v_add_co_u32_e64 v28, s[38:39], s7, v28
	v_add_u32_e32 v0, s78, v0
	s_nop 0
	v_addc_co_u32_e64 v29, s[38:39], 0, v29, s[38:39]
	v_lshl_add_u64 v[14:15], v[14:15], 0, s[10:11]
	v_lshl_add_u64 v[16:17], v[16:17], 0, s[10:11]
	s_waitcnt vmcnt(9)
	v_and_b32_e32 v81, 0xffff0000, v38
	v_and_b32_e32 v83, 0xffff0000, v39
	s_waitcnt vmcnt(8)
	v_and_b32_e32 v85, 0xffff0000, v40
	v_and_b32_e32 v87, 0xffff0000, v41
	v_lshlrev_b32_e32 v80, 16, v38
	v_lshlrev_b32_e32 v82, 16, v39
	v_lshlrev_b32_e32 v84, 16, v40
	v_lshlrev_b32_e32 v86, 16, v41
	s_waitcnt vmcnt(7)
	v_lshlrev_b32_e32 v88, 16, v44
	v_and_b32_e32 v89, 0xffff0000, v44
	v_lshlrev_b32_e32 v90, 16, v45
	v_and_b32_e32 v91, 0xffff0000, v45
	s_waitcnt vmcnt(6)
	v_lshlrev_b32_e32 v92, 16, v46
	v_and_b32_e32 v93, 0xffff0000, v46
	v_lshlrev_b32_e32 v94, 16, v47
	v_and_b32_e32 v95, 0xffff0000, v47
	s_waitcnt vmcnt(4)
	v_lshlrev_b32_e32 v44, 16, v70
	v_and_b32_e32 v45, 0xffff0000, v70
	v_lshlrev_b32_e32 v46, 16, v71
	v_and_b32_e32 v47, 0xffff0000, v71
	v_mul_f32_e32 v42, v81, v81
	v_mul_f32_e32 v57, v83, v83
	v_mul_f32_e32 v70, v85, v85
	v_mul_f32_e32 v71, v87, v87
	s_waitcnt vmcnt(3)
	v_lshlrev_b32_e32 v38, 16, v72
	v_and_b32_e32 v39, 0xffff0000, v72
	v_lshlrev_b32_e32 v40, 16, v73
	v_and_b32_e32 v41, 0xffff0000, v73
	v_mul_f32_e32 v72, v89, v89
	v_mul_f32_e32 v73, v91, v91
	v_fmac_f32_e32 v42, v80, v80
	v_fmac_f32_e32 v57, v82, v82
	v_fmac_f32_e32 v70, v84, v84
	v_fmac_f32_e32 v71, v86, v86
	v_lshlrev_b32_e32 v48, 16, v50
	v_and_b32_e32 v49, 0xffff0000, v50
	v_lshlrev_b32_e32 v50, 16, v51
	v_and_b32_e32 v51, 0xffff0000, v51
	s_waitcnt vmcnt(2)
	v_lshlrev_b32_e32 v30, 16, v74
	v_and_b32_e32 v31, 0xffff0000, v74
	v_lshlrev_b32_e32 v32, 16, v75
	v_and_b32_e32 v33, 0xffff0000, v75
	v_mul_f32_e32 v74, v93, v93
	v_mul_f32_e32 v75, v95, v95
	v_fmac_f32_e32 v72, v88, v88
	v_fmac_f32_e32 v73, v90, v90
	v_add_f32_e32 v42, v42, v57
	v_add_f32_e32 v57, v70, v71
	v_mul_f32_e32 v96, v49, v49
	v_mul_f32_e32 v97, v51, v51
	v_fmac_f32_e32 v74, v92, v92
	v_fmac_f32_e32 v75, v94, v94
	v_add_f32_e32 v70, v72, v73
	v_add_f32_e32 v42, v42, v57
	v_mul_f32_e32 v98, v45, v45
	v_mul_f32_e32 v99, v47, v47
	v_fmac_f32_e32 v96, v48, v48
	v_fmac_f32_e32 v97, v50, v50
	v_add_f32_e32 v71, v74, v75
	v_add_f32_e32 v42, v42, v70
	v_mul_f32_e32 v100, v39, v39
	v_mul_f32_e32 v101, v41, v41
	v_fmac_f32_e32 v98, v44, v44
	v_fmac_f32_e32 v99, v46, v46
	v_add_f32_e32 v72, v96, v97
	v_add_f32_e32 v42, v42, v71
	v_mul_f32_e32 v102, v31, v31
	v_mul_f32_e32 v103, v33, v33
	v_fmac_f32_e32 v100, v38, v38
	v_fmac_f32_e32 v101, v40, v40
	v_add_f32_e32 v73, v98, v99
	v_add_f32_e32 v42, v42, v72
	v_fmac_f32_e32 v102, v30, v30
	v_fmac_f32_e32 v103, v32, v32
	v_add_f32_e32 v74, v100, v101
	v_add_f32_e32 v42, v42, v73
	v_add_f32_e32 v75, v102, v103
	v_add_f32_e32 v42, v42, v74
	v_add_f32_e32 v42, v42, v75
	ds_bpermute_b32 v57, v43, v42
	s_waitcnt vmcnt(1)
	v_pk_add_f32 v[64:65], v[64:65], 1.0 op_sel_hi:[1,0]
	v_pk_add_f32 v[62:63], v[62:63], 1.0 op_sel_hi:[1,0]
	s_waitcnt lgkmcnt(0)
	v_add_f32_e32 v42, v42, v57
	ds_bpermute_b32 v57, v52, v42
	s_waitcnt lgkmcnt(0)
	v_add_f32_e32 v42, v42, v57
	ds_bpermute_b32 v57, v53, v42
	s_waitcnt lgkmcnt(0)
	v_add_f32_e32 v42, v42, v57
	ds_bpermute_b32 v57, v54, v42
	s_waitcnt lgkmcnt(0)
	v_add_f32_e32 v42, v42, v57
	ds_bpermute_b32 v57, v55, v42
	s_waitcnt lgkmcnt(0)
	v_add_f32_e32 v42, v42, v57
	ds_bpermute_b32 v57, v56, v42
	s_waitcnt lgkmcnt(0)
	v_add_f32_e32 v42, v42, v57
	v_fmamk_f32 v42, v42, 0x3a000000, v1
	v_mul_f32_e32 v57, 0x4b800000, v42
	v_cmp_gt_f32_e32 vcc, s1, v42
	s_nop 1
	v_cndmask_b32_e32 v42, v42, v57, vcc
	v_rsq_f32_e32 v42, v42
	s_nop 0
	v_mul_f32_e32 v57, 0x45800000, v42
	v_cndmask_b32_e32 v42, v42, v57, vcc
	v_pk_mul_f32 v[70:71], v[82:83], v[42:43] op_sel_hi:[1,0]
	v_pk_mul_f32 v[72:73], v[80:81], v[42:43] op_sel_hi:[1,0]
	v_pk_mul_f32 v[60:61], v[60:61], v[70:71]
	v_pk_mul_f32 v[58:59], v[58:59], v[72:73]
	s_waitcnt vmcnt(0)
; __device__ __forceinline__ unsigned pk2(float lo, float hi) { return f2bf(lo) | (f2bf(hi) << 16); }
; #define c opq(blockIdx.x)
; __device__ __forceinline__ void phase_norm_mod(const float* srcL, const float* srcC, const float* g, const float* mod_sh, const float* mod_sc, bf16_t* dst, int nrows, const float* part = nullptr, const float* pgate = nullptr, const bf16_t* srcLb = nullptr) {
;     ...
;         for (int j = 0; j < 8; ++j) { const int c = j * 256 + lane * 4; const f32x4 gv = *(const f32x4*)(g + c), shv = *(const f32x4*)(sh + c), scv = *(const f32x4*)(sc + c);
;             const f32x4 y = (v[j] * rstd) * gv; const f32x4 h = y * (scv + 1.f) + shv;
;             u32x2 o; o.x = pk2(h.x, h.y); o.y = pk2(h.z, h.w); *(u32x2*)(dst + (size_t)row * DM + c) = o; }
	v_pk_fma_f32 v[60:61], v[64:65], v[60:61], v[68:69]
	v_pk_fma_f32 v[58:59], v[62:63], v[58:59], v[66:67]
	v_bfe_u32 v63, v60, 16, 1
	v_bfe_u32 v57, v58, 16, 1
	v_bfe_u32 v62, v59, 16, 1
	v_bfe_u32 v64, v61, 16, 1
	v_add3_u32 v57, v58, v57, s6
	v_add3_u32 v58, v59, v62, s6
	v_add3_u32 v59, v60, v63, s6
	v_add3_u32 v60, v61, v64, s6
	v_lshrrev_b32_e32 v57, 16, v57
	v_lshrrev_b32_e32 v59, 16, v59
	v_and_or_b32 v58, v58, s0, v57
	v_and_or_b32 v59, v60, s0, v59
	global_store_dwordx2 v[28:29], v[58:59], off
	v_mov_b32_e32 v58, v120
	v_mov_b32_e32 v59, v121
	v_mov_b32_e32 v60, v122
	v_mov_b32_e32 v61, v123
	s_nop 0
	v_mov_b32_e32 v62, v124
	v_mov_b32_e32 v63, v125
	v_mov_b32_e32 v64, v126
	v_mov_b32_e32 v65, v127
	v_mov_b32_e32 v66, v128
	v_mov_b32_e32 v67, v129
	v_mov_b32_e32 v68, v130
	v_mov_b32_e32 v69, v131
	v_pk_mul_f32 v[74:75], v[86:87], v[42:43] op_sel_hi:[1,0]
	v_pk_mul_f32 v[80:81], v[84:85], v[42:43] op_sel_hi:[1,0]
	v_pk_mul_f32 v[70:71], v[90:91], v[42:43] op_sel_hi:[1,0]
	v_pk_mul_f32 v[72:73], v[88:89], v[42:43] op_sel_hi:[1,0]
	v_pk_mul_f32 v[50:51], v[50:51], v[42:43] op_sel_hi:[1,0]
	v_pk_mul_f32 v[48:49], v[48:49], v[42:43] op_sel_hi:[1,0]
	v_pk_mul_f32 v[46:47], v[46:47], v[42:43] op_sel_hi:[1,0]
	v_pk_mul_f32 v[44:45], v[44:45], v[42:43] op_sel_hi:[1,0]
	v_pk_mul_f32 v[32:33], v[42:43], v[32:33] op_sel_hi:[0,1]
	v_pk_mul_f32 v[30:31], v[42:43], v[30:31] op_sel_hi:[0,1]
	v_cmp_lt_i32_e32 vcc, s14, v0
	s_or_b64 s[12:13], vcc, s[12:13]
	v_pk_mul_f32 v[58:59], v[58:59], v[80:81]
	v_pk_mul_f32 v[60:61], v[60:61], v[74:75]
	v_pk_add_f32 v[64:65], v[64:65], 1.0 op_sel_hi:[1,0]
	v_pk_add_f32 v[62:63], v[62:63], 1.0 op_sel_hi:[1,0]
	v_pk_fma_f32 v[60:61], v[64:65], v[60:61], v[68:69]
	v_pk_fma_f32 v[58:59], v[62:63], v[58:59], v[66:67]
	v_bfe_u32 v63, v60, 16, 1
	v_bfe_u32 v57, v58, 16, 1
	v_bfe_u32 v62, v59, 16, 1
	v_bfe_u32 v64, v61, 16, 1
	v_add3_u32 v57, v58, v57, s6
	v_add3_u32 v58, v59, v62, s6
	v_add3_u32 v59, v60, v63, s6
	v_add3_u32 v60, v61, v64, s6
	v_lshrrev_b32_e32 v57, 16, v57
	v_lshrrev_b32_e32 v59, 16, v59
	v_and_or_b32 v58, v58, s0, v57
	v_and_or_b32 v59, v60, s0, v59
	global_store_dwordx2 v[28:29], v[58:59], off offset:512
	v_mov_b32_e32 v58, v132
	v_mov_b32_e32 v59, v133
	v_mov_b32_e32 v60, v134
	v_mov_b32_e32 v61, v135
	s_nop 0
	v_mov_b32_e32 v62, v136
	v_mov_b32_e32 v63, v137
	v_mov_b32_e32 v64, v138
	v_mov_b32_e32 v65, v139
	v_mov_b32_e32 v66, v140
	v_mov_b32_e32 v67, v141
	v_mov_b32_e32 v68, v142
	v_mov_b32_e32 v69, v143
	v_pk_mul_f32 v[74:75], v[94:95], v[42:43] op_sel_hi:[1,0]
	v_pk_mul_f32 v[58:59], v[58:59], v[72:73]
	v_pk_mul_f32 v[60:61], v[60:61], v[70:71]
	v_pk_add_f32 v[64:65], v[64:65], 1.0 op_sel_hi:[1,0]
	v_pk_add_f32 v[62:63], v[62:63], 1.0 op_sel_hi:[1,0]
	v_pk_fma_f32 v[60:61], v[64:65], v[60:61], v[68:69]
	v_pk_fma_f32 v[58:59], v[62:63], v[58:59], v[66:67]
	v_bfe_u32 v63, v60, 16, 1
	v_bfe_u32 v57, v58, 16, 1
	v_bfe_u32 v62, v59, 16, 1
	v_bfe_u32 v64, v61, 16, 1
	v_add3_u32 v57, v58, v57, s6
	v_add3_u32 v58, v59, v62, s6
	v_add3_u32 v59, v60, v63, s6
	v_add3_u32 v60, v61, v64, s6
	v_lshrrev_b32_e32 v57, 16, v57
	v_lshrrev_b32_e32 v59, 16, v59
	v_and_or_b32 v58, v58, s0, v57
	v_and_or_b32 v59, v60, s0, v59
	global_store_dwordx2 v[28:29], v[58:59], off offset:1024
	v_mov_b32_e32 v58, v144
	v_mov_b32_e32 v59, v145
	v_mov_b32_e32 v60, v146
	v_mov_b32_e32 v61, v147
	s_nop 0
	v_mov_b32_e32 v62, v148
	v_mov_b32_e32 v63, v149
	v_mov_b32_e32 v64, v150
	v_mov_b32_e32 v65, v151
	v_mov_b32_e32 v66, v152
	v_mov_b32_e32 v67, v153
	v_mov_b32_e32 v68, v154
	v_mov_b32_e32 v69, v155
	v_pk_mul_f32 v[76:77], v[92:93], v[42:43] op_sel_hi:[1,0]
	v_lshl_add_u64 v[70:71], v[36:37], 0, v[20:21]
	v_lshl_add_u64 v[72:73], v[34:35], 0, v[20:21]
	v_pk_mul_f32 v[58:59], v[58:59], v[76:77]
	v_pk_mul_f32 v[60:61], v[60:61], v[74:75]
	v_pk_add_f32 v[64:65], v[64:65], 1.0 op_sel_hi:[1,0]
	v_pk_add_f32 v[62:63], v[62:63], 1.0 op_sel_hi:[1,0]
	v_pk_fma_f32 v[60:61], v[64:65], v[60:61], v[68:69]
	v_pk_fma_f32 v[58:59], v[62:63], v[58:59], v[66:67]
	v_bfe_u32 v63, v60, 16, 1
	v_bfe_u32 v57, v58, 16, 1
	v_bfe_u32 v62, v59, 16, 1
	v_bfe_u32 v64, v61, 16, 1
	v_add3_u32 v57, v58, v57, s6
	v_add3_u32 v58, v59, v62, s6
	v_add3_u32 v59, v60, v63, s6
	v_add3_u32 v60, v61, v64, s6
	v_lshrrev_b32_e32 v57, 16, v57
	v_lshrrev_b32_e32 v59, 16, v59
	v_and_or_b32 v58, v58, s0, v57
	v_and_or_b32 v59, v60, s0, v59
	global_store_dwordx2 v[28:29], v[58:59], off offset:1536
	global_load_dwordx4 v[58:61], v[6:7], off
	s_nop 0
	global_load_dwordx4 v[62:65], v[72:73], off
	global_load_dwordx4 v[66:69], v[70:71], off
	v_lshl_add_u64 v[70:71], v[36:37], 0, v[22:23]
	v_lshl_add_u64 v[72:73], v[34:35], 0, v[22:23]
	s_waitcnt vmcnt(2)
; __device__ __forceinline__ unsigned pk2(float lo, float hi) { return f2bf(lo) | (f2bf(hi) << 16); }
; #define c opq(blockIdx.x)
; __device__ __forceinline__ void phase_norm_mod(const float* srcL, const float* srcC, const float* g, const float* mod_sh, const float* mod_sc, bf16_t* dst, int nrows, const float* part = nullptr, const float* pgate = nullptr, const bf16_t* srcLb = nullptr) {
;     ...
;         for (int j = 0; j < 8; ++j) { const int c = j * 256 + lane * 4; const f32x4 gv = *(const f32x4*)(g + c), shv = *(const f32x4*)(sh + c), scv = *(const f32x4*)(sc + c);
;             const f32x4 y = (v[j] * rstd) * gv; const f32x4 h = y * (scv + 1.f) + shv;
;             u32x2 o; o.x = pk2(h.x, h.y); o.y = pk2(h.z, h.w); *(u32x2*)(dst + (size_t)row * DM + c) = o; }
	v_pk_mul_f32 v[48:49], v[58:59], v[48:49]
	v_pk_mul_f32 v[50:51], v[60:61], v[50:51]
	s_waitcnt vmcnt(1)
	v_pk_add_f32 v[58:59], v[64:65], 1.0 op_sel_hi:[1,0]
	v_pk_add_f32 v[60:61], v[62:63], 1.0 op_sel_hi:[1,0]
	s_waitcnt vmcnt(0)
	v_pk_fma_f32 v[50:51], v[50:51], v[58:59], v[68:69]
	v_pk_fma_f32 v[48:49], v[48:49], v[60:61], v[66:67]
	v_bfe_u32 v59, v50, 16, 1
	v_bfe_u32 v57, v48, 16, 1
	v_bfe_u32 v58, v49, 16, 1
	v_bfe_u32 v60, v51, 16, 1
	v_add3_u32 v48, v48, v57, s6
	v_add3_u32 v50, v50, v59, s6
	v_add3_u32 v49, v49, v58, s6
	v_add3_u32 v51, v51, v60, s6
	v_lshrrev_b32_e32 v48, 16, v48
	v_lshrrev_b32_e32 v50, 16, v50
	v_and_or_b32 v48, v49, s0, v48
	v_and_or_b32 v49, v51, s0, v50
	global_store_dwordx2 v[28:29], v[48:49], off offset:2048
	global_load_dwordx4 v[48:51], v[8:9], off
	s_nop 0
	global_load_dwordx4 v[58:61], v[72:73], off
	global_load_dwordx4 v[62:65], v[70:71], off
	v_lshl_add_u64 v[66:67], v[36:37], 0, v[24:25]
	v_lshl_add_u64 v[68:69], v[34:35], 0, v[24:25]
	s_waitcnt vmcnt(2)
	v_pk_mul_f32 v[44:45], v[44:45], v[48:49]
	v_pk_mul_f32 v[46:47], v[46:47], v[50:51]
	s_waitcnt vmcnt(1)
	v_pk_add_f32 v[48:49], v[60:61], 1.0 op_sel_hi:[1,0]
	v_pk_add_f32 v[50:51], v[58:59], 1.0 op_sel_hi:[1,0]
	s_waitcnt vmcnt(0)
	v_pk_fma_f32 v[46:47], v[46:47], v[48:49], v[64:65]
	v_pk_fma_f32 v[44:45], v[44:45], v[50:51], v[62:63]
	v_bfe_u32 v50, v46, 16, 1
	v_bfe_u32 v48, v44, 16, 1
	v_bfe_u32 v49, v45, 16, 1
	v_bfe_u32 v51, v47, 16, 1
	v_add3_u32 v44, v44, v48, s6
	v_add3_u32 v46, v46, v50, s6
	v_add3_u32 v45, v45, v49, s6
	v_add3_u32 v47, v47, v51, s6
	v_lshrrev_b32_e32 v44, 16, v44
	v_lshrrev_b32_e32 v46, 16, v46
	v_and_or_b32 v44, v45, s0, v44
	v_and_or_b32 v45, v47, s0, v46
	global_store_dwordx2 v[28:29], v[44:45], off offset:2560
	global_load_dwordx4 v[44:47], v[10:11], off
	s_nop 0
	global_load_dwordx4 v[48:51], v[68:69], off
	global_load_dwordx4 v[58:61], v[66:67], off
	v_lshl_add_u64 v[62:63], v[36:37], 0, v[26:27]
	v_lshl_add_u64 v[64:65], v[34:35], 0, v[26:27]
	v_pk_mul_f32 v[34:35], v[42:43], v[40:41] op_sel_hi:[0,1]
	v_pk_mul_f32 v[36:37], v[42:43], v[38:39] op_sel_hi:[0,1]
	s_waitcnt vmcnt(2)
	v_pk_mul_f32 v[36:37], v[36:37], v[44:45]
	v_pk_mul_f32 v[34:35], v[34:35], v[46:47]
	s_waitcnt vmcnt(1)
	v_pk_add_f32 v[38:39], v[50:51], 1.0 op_sel_hi:[1,0]
	v_pk_add_f32 v[40:41], v[48:49], 1.0 op_sel_hi:[1,0]
	s_waitcnt vmcnt(0)
	v_pk_fma_f32 v[34:35], v[34:35], v[38:39], v[60:61]
	v_pk_fma_f32 v[36:37], v[36:37], v[40:41], v[58:59]
	v_bfe_u32 v40, v34, 16, 1
	v_bfe_u32 v38, v36, 16, 1
	v_bfe_u32 v39, v37, 16, 1
	v_bfe_u32 v41, v35, 16, 1
	v_add3_u32 v36, v36, v38, s6
	v_add3_u32 v34, v34, v40, s6
	v_add3_u32 v37, v37, v39, s6
	v_add3_u32 v35, v35, v41, s6
	v_lshrrev_b32_e32 v36, 16, v36
	v_lshrrev_b32_e32 v38, 16, v34
	v_and_or_b32 v34, v37, s0, v36
	v_and_or_b32 v35, v35, s0, v38
	global_store_dwordx2 v[28:29], v[34:35], off offset:3072
	global_load_dwordx4 v[34:37], v[12:13], off
	s_nop 0
	global_load_dwordx4 v[38:41], v[64:65], off
	global_load_dwordx4 v[44:47], v[62:63], off
	s_waitcnt vmcnt(2)
	v_pk_mul_f32 v[30:31], v[30:31], v[34:35]
	v_pk_mul_f32 v[32:33], v[32:33], v[36:37]
	s_waitcnt vmcnt(1)
	v_pk_add_f32 v[34:35], v[40:41], 1.0 op_sel_hi:[1,0]
	v_pk_add_f32 v[36:37], v[38:39], 1.0 op_sel_hi:[1,0]
	s_waitcnt vmcnt(0)
	v_pk_fma_f32 v[32:33], v[32:33], v[34:35], v[46:47]
	v_pk_fma_f32 v[30:31], v[30:31], v[36:37], v[44:45]
	v_bfe_u32 v36, v32, 16, 1
	v_bfe_u32 v34, v30, 16, 1
	v_bfe_u32 v35, v31, 16, 1
	v_bfe_u32 v37, v33, 16, 1
	v_add3_u32 v30, v30, v34, s6
	v_add3_u32 v32, v32, v36, s6
	v_add3_u32 v31, v31, v35, s6
	v_add3_u32 v33, v33, v37, s6
	v_lshrrev_b32_e32 v30, 16, v30
	v_lshrrev_b32_e32 v32, 16, v32
	v_and_or_b32 v30, v31, s0, v30
	v_and_or_b32 v31, v33, s0, v32
	global_store_dwordx2 v[28:29], v[30:31], off offset:3584
	s_andn2_b64 exec, exec, s[12:13]
	s_cbranch_execnz .LBB0_2178
